# removed no-op lgkmcnt waits and mid-block setprio pairs inside the MFMA blocks of all GEMM K-loops (on top of attention staging)
# speedup vs baseline: 1.0113x; 1.0113x over previous
.LBB0_269:
	ds_read_b128 v[16:19], v185
	ds_read_b128 v[24:27], v185 offset:2048
	ds_read_b128 v[20:23], v186
	ds_read_b128 v[28:31], v186 offset:2048
	ds_read_b128 v[0:3], v187
	ds_read_b128 v[8:11], v187 offset:2048
	ds_read_b128 v[4:7], v188
	ds_read_b128 v[12:15], v188 offset:2048
	s_add_u32 s44, s8, 0x100
	s_addc_u32 s45, s9, 0
	s_cmp_eq_u32 s72, 28
	s_cselect_b32 s50, s7, s44
	s_cselect_b32 s51, s1, s45
	s_cselect_b32 s48, s33, s37
	s_cselect_b32 s49, s11, s39
	s_add_u32 s46, s50, 0x80
	s_addc_u32 s47, s51, 0
	ds_read_b128 v[160:163], v189
	ds_read_b128 v[172:175], v189 offset:2048
	ds_read_b128 v[164:167], v190
	ds_read_b128 v[176:179], v190 offset:2048
	ds_read_b128 v[212:215], v189 offset:4096
	ds_read_b128 v[226:229], v189 offset:6144
	ds_read_b128 v[216:219], v190 offset:4096
	ds_read_b128 v[230:233], v190 offset:6144
	s_add_u32 s8, s8, 0x80080
	s_addc_u32 s9, s9, 0
	s_add_i32 m0, s27, 0xc000
	s_nop 0
	global_load_lds_dwordx4 v180, s[8:9]
	s_nop 0
	s_add_i32 m0, s27, 0xe000
	s_nop 0
	global_load_lds_dwordx4 v181, s[8:9]
	s_waitcnt vmcnt(8)
	s_waitcnt lgkmcnt(0)
	s_barrier
	s_setprio 1
	v_mfma_scale_f32_16x16x128_f8f6f4 v[156:159], v[16:23], v[160:167], v[156:159], v182, v182 op_sel_hi:[0,0,0]
	v_mfma_scale_f32_16x16x128_f8f6f4 v[152:155], v[24:31], v[160:167], v[152:155], v182, v182 op_sel_hi:[0,0,0]
	v_mfma_scale_f32_16x16x128_f8f6f4 v[140:143], v[16:23], v[172:179], v[140:143], v182, v182 op_sel_hi:[0,0,0]
	v_mfma_scale_f32_16x16x128_f8f6f4 v[136:139], v[24:31], v[172:179], v[136:139], v182, v182 op_sel_hi:[0,0,0]
	v_mfma_scale_f32_16x16x128_f8f6f4 v[124:127], v[16:23], v[212:219], v[124:127], v182, v182 op_sel_hi:[0,0,0]
	v_mfma_scale_f32_16x16x128_f8f6f4 v[120:123], v[24:31], v[212:219], v[120:123], v182, v182 op_sel_hi:[0,0,0]
	v_mfma_scale_f32_16x16x128_f8f6f4 v[108:111], v[16:23], v[226:233], v[108:111], v182, v182 op_sel_hi:[0,0,0]
	v_mfma_scale_f32_16x16x128_f8f6f4 v[104:107], v[24:31], v[226:233], v[104:107], v182, v182 op_sel_hi:[0,0,0]
	v_mfma_scale_f32_16x16x128_f8f6f4 v[148:151], v[0:7], v[160:167], v[148:151], v182, v182 op_sel_hi:[0,0,0]
	v_mfma_scale_f32_16x16x128_f8f6f4 v[144:147], v[8:15], v[160:167], v[144:147], v182, v182 op_sel_hi:[0,0,0]
	v_mfma_scale_f32_16x16x128_f8f6f4 v[132:135], v[0:7], v[172:179], v[132:135], v182, v182 op_sel_hi:[0,0,0]
	v_mfma_scale_f32_16x16x128_f8f6f4 v[128:131], v[8:15], v[172:179], v[128:131], v182, v182 op_sel_hi:[0,0,0]
	v_mfma_scale_f32_16x16x128_f8f6f4 v[116:119], v[0:7], v[212:219], v[116:119], v182, v182 op_sel_hi:[0,0,0]
	v_mfma_scale_f32_16x16x128_f8f6f4 v[112:115], v[8:15], v[212:219], v[112:115], v182, v182 op_sel_hi:[0,0,0]
	v_mfma_scale_f32_16x16x128_f8f6f4 v[100:103], v[0:7], v[226:233], v[100:103], v182, v182 op_sel_hi:[0,0,0]
	v_mfma_scale_f32_16x16x128_f8f6f4 v[96:99], v[8:15], v[226:233], v[96:99], v182, v182 op_sel_hi:[0,0,0]
	s_setprio 0
	s_barrier
	ds_read_b128 v[160:163], v189 offset:16384
	ds_read_b128 v[172:175], v189 offset:18432
	ds_read_b128 v[164:167], v190 offset:16384
	ds_read_b128 v[176:179], v190 offset:18432
	ds_read_b128 v[212:215], v189 offset:20480
	ds_read_b128 v[226:229], v189 offset:22528
	ds_read_b128 v[216:219], v190 offset:20480
	ds_read_b128 v[230:233], v190 offset:22528
	s_add_i32 m0, s27, 0x10000
	s_nop 0
	global_load_lds_dwordx4 v180, s[48:49]
	s_nop 0
	s_add_i32 m0, s27, 0x12000
	s_nop 0
	global_load_lds_dwordx4 v181, s[48:49]
	s_add_u32 s8, s48, 0x80000
	s_addc_u32 s9, s49, 0
	s_add_i32 m0, s27, 0x14000
	s_nop 0
	global_load_lds_dwordx4 v180, s[8:9]
	s_nop 0
	s_add_i32 m0, s27, 0x16000
	s_nop 0
	global_load_lds_dwordx4 v181, s[8:9]
	s_nop 0
	s_add_i32 m0, s27, 0
	s_nop 0
	global_load_lds_dwordx4 v180, s[50:51]
	s_nop 0
	s_add_i32 m0, s27, 0x2000
	s_nop 0
	global_load_lds_dwordx4 v181, s[50:51]
	s_waitcnt vmcnt(8)
	s_waitcnt lgkmcnt(0)
	s_barrier
	s_setprio 1
	v_mfma_scale_f32_16x16x128_f8f6f4 v[92:95], v[16:23], v[160:167], v[92:95], v182, v182 op_sel_hi:[0,0,0]
	v_mfma_scale_f32_16x16x128_f8f6f4 v[88:91], v[24:31], v[160:167], v[88:91], v182, v182 op_sel_hi:[0,0,0]
	v_mfma_scale_f32_16x16x128_f8f6f4 v[76:79], v[16:23], v[172:179], v[76:79], v182, v182 op_sel_hi:[0,0,0]
	v_mfma_scale_f32_16x16x128_f8f6f4 v[72:75], v[24:31], v[172:179], v[72:75], v182, v182 op_sel_hi:[0,0,0]
	v_mfma_scale_f32_16x16x128_f8f6f4 v[60:63], v[16:23], v[212:219], v[60:63], v182, v182 op_sel_hi:[0,0,0]
	v_mfma_scale_f32_16x16x128_f8f6f4 v[56:59], v[24:31], v[212:219], v[56:59], v182, v182 op_sel_hi:[0,0,0]
	v_mfma_scale_f32_16x16x128_f8f6f4 v[44:47], v[16:23], v[226:233], v[44:47], v182, v182 op_sel_hi:[0,0,0]
	v_mfma_scale_f32_16x16x128_f8f6f4 v[40:43], v[24:31], v[226:233], v[40:43], v182, v182 op_sel_hi:[0,0,0]
	v_mfma_scale_f32_16x16x128_f8f6f4 v[84:87], v[0:7], v[160:167], v[84:87], v182, v182 op_sel_hi:[0,0,0]
	v_mfma_scale_f32_16x16x128_f8f6f4 v[80:83], v[8:15], v[160:167], v[80:83], v182, v182 op_sel_hi:[0,0,0]
	v_mfma_scale_f32_16x16x128_f8f6f4 v[68:71], v[0:7], v[172:179], v[68:71], v182, v182 op_sel_hi:[0,0,0]
	v_mfma_scale_f32_16x16x128_f8f6f4 v[64:67], v[8:15], v[172:179], v[64:67], v182, v182 op_sel_hi:[0,0,0]
	v_mfma_scale_f32_16x16x128_f8f6f4 v[52:55], v[0:7], v[212:219], v[52:55], v182, v182 op_sel_hi:[0,0,0]
	v_mfma_scale_f32_16x16x128_f8f6f4 v[48:51], v[8:15], v[212:219], v[48:51], v182, v182 op_sel_hi:[0,0,0]
	v_mfma_scale_f32_16x16x128_f8f6f4 v[36:39], v[0:7], v[226:233], v[36:39], v182, v182 op_sel_hi:[0,0,0]
	v_mfma_scale_f32_16x16x128_f8f6f4 v[32:35], v[8:15], v[226:233], v[32:35], v182, v182 op_sel_hi:[0,0,0]
	s_setprio 0
	s_barrier
	ds_read_b128 v[0:3], v191
	ds_read_b128 v[8:11], v191 offset:2048
	ds_read_b128 v[4:7], v192
	ds_read_b128 v[12:15], v192 offset:2048
	ds_read_b128 v[16:19], v193
	ds_read_b128 v[24:27], v193 offset:2048
	ds_read_b128 v[20:23], v194
	ds_read_b128 v[28:31], v194 offset:2048
	ds_read_b128 v[160:163], v189 offset:32768
	ds_read_b128 v[172:175], v189 offset:34816
	ds_read_b128 v[164:167], v190 offset:32768
	ds_read_b128 v[176:179], v190 offset:34816
	ds_read_b128 v[212:215], v189 offset:36864
	ds_read_b128 v[226:229], v189 offset:38912
	ds_read_b128 v[216:219], v190 offset:36864
	ds_read_b128 v[230:233], v190 offset:38912
	s_add_u32 s8, s50, 0x80000
	s_addc_u32 s9, s51, 0
	s_add_i32 m0, s27, 0x4000
	s_nop 0
	global_load_lds_dwordx4 v180, s[8:9]
	s_nop 0
	s_add_i32 m0, s27, 0x6000
	s_nop 0
	global_load_lds_dwordx4 v181, s[8:9]
	s_waitcnt vmcnt(8)
	s_waitcnt lgkmcnt(0)
	s_barrier
	s_setprio 1
	v_mfma_scale_f32_16x16x128_f8f6f4 v[156:159], v[0:7], v[160:167], v[156:159], v182, v182 op_sel_hi:[0,0,0]
	v_mfma_scale_f32_16x16x128_f8f6f4 v[152:155], v[8:15], v[160:167], v[152:155], v182, v182 op_sel_hi:[0,0,0]
	v_mfma_scale_f32_16x16x128_f8f6f4 v[140:143], v[0:7], v[172:179], v[140:143], v182, v182 op_sel_hi:[0,0,0]
	v_mfma_scale_f32_16x16x128_f8f6f4 v[136:139], v[8:15], v[172:179], v[136:139], v182, v182 op_sel_hi:[0,0,0]
	v_mfma_scale_f32_16x16x128_f8f6f4 v[124:127], v[0:7], v[212:219], v[124:127], v182, v182 op_sel_hi:[0,0,0]
	v_mfma_scale_f32_16x16x128_f8f6f4 v[120:123], v[8:15], v[212:219], v[120:123], v182, v182 op_sel_hi:[0,0,0]
	v_mfma_scale_f32_16x16x128_f8f6f4 v[108:111], v[0:7], v[226:233], v[108:111], v182, v182 op_sel_hi:[0,0,0]
	v_mfma_scale_f32_16x16x128_f8f6f4 v[104:107], v[8:15], v[226:233], v[104:107], v182, v182 op_sel_hi:[0,0,0]
	v_mfma_scale_f32_16x16x128_f8f6f4 v[148:151], v[16:23], v[160:167], v[148:151], v182, v182 op_sel_hi:[0,0,0]
	v_mfma_scale_f32_16x16x128_f8f6f4 v[144:147], v[24:31], v[160:167], v[144:147], v182, v182 op_sel_hi:[0,0,0]
	v_mfma_scale_f32_16x16x128_f8f6f4 v[132:135], v[16:23], v[172:179], v[132:135], v182, v182 op_sel_hi:[0,0,0]
	v_mfma_scale_f32_16x16x128_f8f6f4 v[128:131], v[24:31], v[172:179], v[128:131], v182, v182 op_sel_hi:[0,0,0]
	v_mfma_scale_f32_16x16x128_f8f6f4 v[116:119], v[16:23], v[212:219], v[116:119], v182, v182 op_sel_hi:[0,0,0]
	v_mfma_scale_f32_16x16x128_f8f6f4 v[112:115], v[24:31], v[212:219], v[112:115], v182, v182 op_sel_hi:[0,0,0]
	v_mfma_scale_f32_16x16x128_f8f6f4 v[100:103], v[16:23], v[226:233], v[100:103], v182, v182 op_sel_hi:[0,0,0]
	v_mfma_scale_f32_16x16x128_f8f6f4 v[96:99], v[24:31], v[226:233], v[96:99], v182, v182 op_sel_hi:[0,0,0]
	s_setprio 0
	s_barrier
	s_add_u32 s8, s48, 0x80
	ds_read_b128 v[160:163], v189 offset:49152
	ds_read_b128 v[172:175], v189 offset:51200
	ds_read_b128 v[164:167], v190 offset:49152
	ds_read_b128 v[176:179], v190 offset:51200
	ds_read_b128 v[212:215], v189 offset:53248
	ds_read_b128 v[226:229], v189 offset:55296
	ds_read_b128 v[216:219], v190 offset:53248
	ds_read_b128 v[230:233], v190 offset:55296
	s_addc_u32 s9, s49, 0
	s_add_i32 m0, s27, 0x18000
	s_nop 0
	global_load_lds_dwordx4 v180, s[8:9]
	s_nop 0
	s_add_i32 m0, s27, 0x1a000
	s_nop 0
	global_load_lds_dwordx4 v181, s[8:9]
	s_add_u32 s8, s48, 0x80080
	s_addc_u32 s9, s49, 0
	s_add_i32 m0, s27, 0x1c000
	s_nop 0
	global_load_lds_dwordx4 v180, s[8:9]
	s_nop 0
	s_add_i32 m0, s27, 0x1e000
	s_nop 0
	global_load_lds_dwordx4 v181, s[8:9]
	s_nop 0
	s_add_i32 m0, s27, 0x8000
	s_nop 0
	global_load_lds_dwordx4 v180, s[46:47]
	s_nop 0
	s_add_i32 m0, s27, 0xa000
	s_nop 0
	global_load_lds_dwordx4 v181, s[46:47]
	s_waitcnt vmcnt(8)
	s_waitcnt lgkmcnt(0)
	s_barrier
	s_setprio 1
	v_mfma_scale_f32_16x16x128_f8f6f4 v[92:95], v[0:7], v[160:167], v[92:95], v182, v182 op_sel_hi:[0,0,0]
	v_mfma_scale_f32_16x16x128_f8f6f4 v[88:91], v[8:15], v[160:167], v[88:91], v182, v182 op_sel_hi:[0,0,0]
	v_mfma_scale_f32_16x16x128_f8f6f4 v[76:79], v[0:7], v[172:179], v[76:79], v182, v182 op_sel_hi:[0,0,0]
	v_mfma_scale_f32_16x16x128_f8f6f4 v[72:75], v[8:15], v[172:179], v[72:75], v182, v182 op_sel_hi:[0,0,0]
	v_mfma_scale_f32_16x16x128_f8f6f4 v[60:63], v[0:7], v[212:219], v[60:63], v182, v182 op_sel_hi:[0,0,0]
	v_mfma_scale_f32_16x16x128_f8f6f4 v[56:59], v[8:15], v[212:219], v[56:59], v182, v182 op_sel_hi:[0,0,0]
	v_mfma_scale_f32_16x16x128_f8f6f4 v[44:47], v[0:7], v[226:233], v[44:47], v182, v182 op_sel_hi:[0,0,0]
	v_mfma_scale_f32_16x16x128_f8f6f4 v[40:43], v[8:15], v[226:233], v[40:43], v182, v182 op_sel_hi:[0,0,0]
	v_mfma_scale_f32_16x16x128_f8f6f4 v[84:87], v[16:23], v[160:167], v[84:87], v182, v182 op_sel_hi:[0,0,0]
	v_mfma_scale_f32_16x16x128_f8f6f4 v[80:83], v[24:31], v[160:167], v[80:83], v182, v182 op_sel_hi:[0,0,0]
	v_mfma_scale_f32_16x16x128_f8f6f4 v[68:71], v[16:23], v[172:179], v[68:71], v182, v182 op_sel_hi:[0,0,0]
	v_mfma_scale_f32_16x16x128_f8f6f4 v[64:67], v[24:31], v[172:179], v[64:67], v182, v182 op_sel_hi:[0,0,0]
	v_mfma_scale_f32_16x16x128_f8f6f4 v[52:55], v[16:23], v[212:219], v[52:55], v182, v182 op_sel_hi:[0,0,0]
	v_mfma_scale_f32_16x16x128_f8f6f4 v[48:51], v[24:31], v[212:219], v[48:51], v182, v182 op_sel_hi:[0,0,0]
	v_mfma_scale_f32_16x16x128_f8f6f4 v[36:39], v[16:23], v[226:233], v[36:39], v182, v182 op_sel_hi:[0,0,0]
	v_mfma_scale_f32_16x16x128_f8f6f4 v[32:35], v[24:31], v[226:233], v[32:35], v182, v182 op_sel_hi:[0,0,0]
	s_setprio 0
	s_barrier
	s_add_i32 s72, s72, 2
	s_add_u32 s37, s37, 0x100
	s_addc_u32 s39, s39, 0
	s_cmp_gt_u32 s72, 29
	s_mov_b64 s[8:9], s[44:45]
	s_cbranch_scc0 .LBB0_269
	s_and_b64 vcc, exec, s[24:25]
	s_cbranch_vccz .LBB0_272
	s_barrier

.LBB0_339:
	ds_read_b128 v[156:159], v166
	ds_read_b128 v[152:155], v166 offset:1024
	ds_read_b128 v[148:151], v166 offset:2048
	ds_read_b128 v[144:147], v166 offset:3072
	ds_read_b128 v[140:143], v167
	ds_read_b128 v[136:139], v167 offset:1024
	ds_read_b128 v[132:135], v167 offset:2048
	ds_read_b128 v[128:131], v167 offset:3072
	s_add_u32 s36, s38, 0x100
	s_addc_u32 s37, s39, 0
	s_cmp_eq_u32 s62, 28
	s_cselect_b32 s44, s58, s36
	s_cselect_b32 s45, s27, s37
	s_cselect_b32 s42, s59, s60
	s_cselect_b32 s43, s25, s61
	s_add_u32 s40, s44, 0x80
	s_addc_u32 s41, s45, 0
	ds_read_b128 v[172:175], v168
	ds_read_b128 v[176:179], v168 offset:1024
	ds_read_b128 v[180:183], v168 offset:2048
	ds_read_b128 v[184:187], v168 offset:3072
	ds_read_b128 v[188:191], v168 offset:4096
	ds_read_b128 v[192:195], v168 offset:5120
	ds_read_b128 v[196:199], v168 offset:6144
	ds_read_b128 v[200:203], v168 offset:7168
	s_add_u32 s38, s38, 0x80080
	s_addc_u32 s39, s39, 0
	s_add_i32 m0, s1, 0xc000
	s_nop 0
	global_load_lds_dwordx4 v164, s[38:39]
	s_nop 0
	s_add_i32 m0, s1, 0xe000
	s_nop 0
	global_load_lds_dwordx4 v165, s[38:39]
	s_waitcnt vmcnt(8)
	s_waitcnt lgkmcnt(0)
	s_barrier
	s_setprio 1
	v_mfma_i32_16x16x64_i8 v[124:127], v[156:159], v[172:175], v[124:127]
	v_mfma_i32_16x16x64_i8 v[124:127], v[152:155], v[176:179], v[124:127]
	v_mfma_i32_16x16x64_i8 v[120:123], v[148:151], v[172:175], v[120:123]
	s_nop 0
	v_mfma_i32_16x16x64_i8 v[120:123], v[144:147], v[176:179], v[120:123]
	v_mfma_i32_16x16x64_i8 v[108:111], v[156:159], v[180:183], v[108:111]
	v_mfma_i32_16x16x64_i8 v[108:111], v[152:155], v[184:187], v[108:111]
	v_mfma_i32_16x16x64_i8 v[104:107], v[148:151], v[180:183], v[104:107]
	s_nop 0
	v_mfma_i32_16x16x64_i8 v[104:107], v[144:147], v[184:187], v[104:107]
	v_mfma_i32_16x16x64_i8 v[92:95], v[156:159], v[188:191], v[92:95]
	v_mfma_i32_16x16x64_i8 v[92:95], v[152:155], v[192:195], v[92:95]
	v_mfma_i32_16x16x64_i8 v[88:91], v[148:151], v[188:191], v[88:91]
	s_nop 0
	v_mfma_i32_16x16x64_i8 v[88:91], v[144:147], v[192:195], v[88:91]
	v_mfma_i32_16x16x64_i8 v[76:79], v[156:159], v[196:199], v[76:79]
	v_mfma_i32_16x16x64_i8 v[76:79], v[152:155], v[200:203], v[76:79]
	v_mfma_i32_16x16x64_i8 v[72:75], v[148:151], v[196:199], v[72:75]
	s_nop 0
	v_mfma_i32_16x16x64_i8 v[72:75], v[144:147], v[200:203], v[72:75]
	v_mfma_i32_16x16x64_i8 v[116:119], v[140:143], v[172:175], v[116:119]
	s_nop 0
	v_mfma_i32_16x16x64_i8 v[116:119], v[136:139], v[176:179], v[116:119]
	v_mfma_i32_16x16x64_i8 v[112:115], v[132:135], v[172:175], v[112:115]
	s_nop 0
	v_mfma_i32_16x16x64_i8 v[112:115], v[128:131], v[176:179], v[112:115]
	v_mfma_i32_16x16x64_i8 v[100:103], v[140:143], v[180:183], v[100:103]
	s_nop 0
	v_mfma_i32_16x16x64_i8 v[100:103], v[136:139], v[184:187], v[100:103]
	v_mfma_i32_16x16x64_i8 v[96:99], v[132:135], v[180:183], v[96:99]
	s_nop 0
	v_mfma_i32_16x16x64_i8 v[96:99], v[128:131], v[184:187], v[96:99]
	v_mfma_i32_16x16x64_i8 v[84:87], v[140:143], v[188:191], v[84:87]
	s_nop 0
	v_mfma_i32_16x16x64_i8 v[84:87], v[136:139], v[192:195], v[84:87]
	v_mfma_i32_16x16x64_i8 v[80:83], v[132:135], v[188:191], v[80:83]
	s_nop 0
	v_mfma_i32_16x16x64_i8 v[80:83], v[128:131], v[192:195], v[80:83]
	v_mfma_i32_16x16x64_i8 v[68:71], v[140:143], v[196:199], v[68:71]
	s_nop 0
	v_mfma_i32_16x16x64_i8 v[68:71], v[136:139], v[200:203], v[68:71]
	v_mfma_i32_16x16x64_i8 v[64:67], v[132:135], v[196:199], v[64:67]
	s_nop 0
	v_mfma_i32_16x16x64_i8 v[64:67], v[128:131], v[200:203], v[64:67]
	s_setprio 0
	s_barrier
	ds_read_b128 v[172:175], v168 offset:16384
	ds_read_b128 v[176:179], v168 offset:17408
	ds_read_b128 v[180:183], v168 offset:18432
	ds_read_b128 v[184:187], v168 offset:19456
	ds_read_b128 v[188:191], v168 offset:20480
	ds_read_b128 v[192:195], v168 offset:21504
	ds_read_b128 v[196:199], v168 offset:22528
	ds_read_b128 v[200:203], v168 offset:23552
	s_add_i32 m0, s1, 0x10000
	s_nop 0
	global_load_lds_dwordx4 v164, s[42:43]
	s_nop 0
	s_add_i32 m0, s1, 0x12000
	s_nop 0
	global_load_lds_dwordx4 v165, s[42:43]
	s_add_u32 s38, s42, 0x80000
	s_addc_u32 s39, s43, 0
	s_add_i32 m0, s1, 0x14000
	s_nop 0
	global_load_lds_dwordx4 v164, s[38:39]
	s_nop 0
	s_add_i32 m0, s1, 0x16000
	s_nop 0
	global_load_lds_dwordx4 v165, s[38:39]
	s_nop 0
	s_add_i32 m0, s1, 0
	s_nop 0
	global_load_lds_dwordx4 v164, s[44:45]
	s_nop 0
	s_add_i32 m0, s1, 0x2000
	s_nop 0
	global_load_lds_dwordx4 v165, s[44:45]
	s_waitcnt vmcnt(8)
	s_waitcnt lgkmcnt(0)
	s_barrier
	s_setprio 1
	v_mfma_i32_16x16x64_i8 v[60:63], v[156:159], v[172:175], v[60:63]
	v_mfma_i32_16x16x64_i8 v[60:63], v[152:155], v[176:179], v[60:63]
	v_mfma_i32_16x16x64_i8 v[56:59], v[148:151], v[172:175], v[56:59]
	s_nop 0
	v_mfma_i32_16x16x64_i8 v[56:59], v[144:147], v[176:179], v[56:59]
	v_mfma_i32_16x16x64_i8 v[44:47], v[156:159], v[180:183], v[44:47]
	v_mfma_i32_16x16x64_i8 v[44:47], v[152:155], v[184:187], v[44:47]
	v_mfma_i32_16x16x64_i8 v[40:43], v[148:151], v[180:183], v[40:43]
	s_nop 0
	v_mfma_i32_16x16x64_i8 v[40:43], v[144:147], v[184:187], v[40:43]
	v_mfma_i32_16x16x64_i8 v[28:31], v[156:159], v[188:191], v[28:31]
	v_mfma_i32_16x16x64_i8 v[28:31], v[152:155], v[192:195], v[28:31]
	v_mfma_i32_16x16x64_i8 v[24:27], v[148:151], v[188:191], v[24:27]
	s_nop 0
	v_mfma_i32_16x16x64_i8 v[24:27], v[144:147], v[192:195], v[24:27]
	v_mfma_i32_16x16x64_i8 v[12:15], v[156:159], v[196:199], v[12:15]
	v_mfma_i32_16x16x64_i8 v[12:15], v[152:155], v[200:203], v[12:15]
	v_mfma_i32_16x16x64_i8 v[8:11], v[148:151], v[196:199], v[8:11]
	s_nop 0
	v_mfma_i32_16x16x64_i8 v[8:11], v[144:147], v[200:203], v[8:11]
	v_mfma_i32_16x16x64_i8 v[52:55], v[140:143], v[172:175], v[52:55]
	s_nop 0
	v_mfma_i32_16x16x64_i8 v[52:55], v[136:139], v[176:179], v[52:55]
	v_mfma_i32_16x16x64_i8 v[48:51], v[132:135], v[172:175], v[48:51]
	s_nop 0
	v_mfma_i32_16x16x64_i8 v[48:51], v[128:131], v[176:179], v[48:51]
	v_mfma_i32_16x16x64_i8 v[36:39], v[140:143], v[180:183], v[36:39]
	s_nop 0
	v_mfma_i32_16x16x64_i8 v[36:39], v[136:139], v[184:187], v[36:39]
	v_mfma_i32_16x16x64_i8 v[32:35], v[132:135], v[180:183], v[32:35]
	s_nop 0
	v_mfma_i32_16x16x64_i8 v[32:35], v[128:131], v[184:187], v[32:35]
	v_mfma_i32_16x16x64_i8 v[20:23], v[140:143], v[188:191], v[20:23]
	s_nop 0
	v_mfma_i32_16x16x64_i8 v[20:23], v[136:139], v[192:195], v[20:23]
	v_mfma_i32_16x16x64_i8 v[16:19], v[132:135], v[188:191], v[16:19]
	s_nop 0
	v_mfma_i32_16x16x64_i8 v[16:19], v[128:131], v[192:195], v[16:19]
	v_mfma_i32_16x16x64_i8 v[4:7], v[140:143], v[196:199], v[4:7]
	s_nop 0
	v_mfma_i32_16x16x64_i8 v[4:7], v[136:139], v[200:203], v[4:7]
	v_mfma_i32_16x16x64_i8 v[0:3], v[132:135], v[196:199], v[0:3]
	s_nop 0
	v_mfma_i32_16x16x64_i8 v[0:3], v[128:131], v[200:203], v[0:3]
	s_setprio 0
	s_barrier
	ds_read_b128 v[128:131], v169
	ds_read_b128 v[132:135], v169 offset:1024
	ds_read_b128 v[136:139], v169 offset:2048
	ds_read_b128 v[140:143], v169 offset:3072
	ds_read_b128 v[144:147], v170
	ds_read_b128 v[148:151], v170 offset:1024
	ds_read_b128 v[152:155], v170 offset:2048
	ds_read_b128 v[156:159], v170 offset:3072
	ds_read_b128 v[172:175], v168 offset:32768
	ds_read_b128 v[176:179], v168 offset:33792
	ds_read_b128 v[180:183], v168 offset:34816
	ds_read_b128 v[184:187], v168 offset:35840
	ds_read_b128 v[188:191], v168 offset:36864
	ds_read_b128 v[192:195], v168 offset:37888
	ds_read_b128 v[196:199], v168 offset:38912
	ds_read_b128 v[200:203], v168 offset:39936
	s_add_u32 s38, s44, 0x80000
	s_addc_u32 s39, s45, 0
	s_add_i32 m0, s1, 0x4000
	s_nop 0
	global_load_lds_dwordx4 v164, s[38:39]
	s_nop 0
	s_add_i32 m0, s1, 0x6000
	s_nop 0
	global_load_lds_dwordx4 v165, s[38:39]
	s_waitcnt vmcnt(8)
	s_waitcnt lgkmcnt(0)
	s_barrier
	s_setprio 1
	v_mfma_i32_16x16x64_i8 v[124:127], v[128:131], v[172:175], v[124:127]
	v_mfma_i32_16x16x64_i8 v[124:127], v[132:135], v[176:179], v[124:127]
	v_mfma_i32_16x16x64_i8 v[120:123], v[136:139], v[172:175], v[120:123]
	s_nop 0
	v_mfma_i32_16x16x64_i8 v[120:123], v[140:143], v[176:179], v[120:123]
	v_mfma_i32_16x16x64_i8 v[108:111], v[128:131], v[180:183], v[108:111]
	v_mfma_i32_16x16x64_i8 v[108:111], v[132:135], v[184:187], v[108:111]
	v_mfma_i32_16x16x64_i8 v[104:107], v[136:139], v[180:183], v[104:107]
	s_nop 0
	v_mfma_i32_16x16x64_i8 v[104:107], v[140:143], v[184:187], v[104:107]
	v_mfma_i32_16x16x64_i8 v[92:95], v[128:131], v[188:191], v[92:95]
	v_mfma_i32_16x16x64_i8 v[92:95], v[132:135], v[192:195], v[92:95]
	v_mfma_i32_16x16x64_i8 v[88:91], v[136:139], v[188:191], v[88:91]
	s_nop 0
	v_mfma_i32_16x16x64_i8 v[88:91], v[140:143], v[192:195], v[88:91]
	v_mfma_i32_16x16x64_i8 v[76:79], v[128:131], v[196:199], v[76:79]
	v_mfma_i32_16x16x64_i8 v[76:79], v[132:135], v[200:203], v[76:79]
	v_mfma_i32_16x16x64_i8 v[72:75], v[136:139], v[196:199], v[72:75]
	s_nop 0
	v_mfma_i32_16x16x64_i8 v[72:75], v[140:143], v[200:203], v[72:75]
	v_mfma_i32_16x16x64_i8 v[116:119], v[144:147], v[172:175], v[116:119]
	s_nop 0
	v_mfma_i32_16x16x64_i8 v[116:119], v[148:151], v[176:179], v[116:119]
	v_mfma_i32_16x16x64_i8 v[112:115], v[152:155], v[172:175], v[112:115]
	s_nop 0
	v_mfma_i32_16x16x64_i8 v[112:115], v[156:159], v[176:179], v[112:115]
	v_mfma_i32_16x16x64_i8 v[100:103], v[144:147], v[180:183], v[100:103]
	s_nop 0
	v_mfma_i32_16x16x64_i8 v[100:103], v[148:151], v[184:187], v[100:103]
	v_mfma_i32_16x16x64_i8 v[96:99], v[152:155], v[180:183], v[96:99]
	s_nop 0
	v_mfma_i32_16x16x64_i8 v[96:99], v[156:159], v[184:187], v[96:99]
	v_mfma_i32_16x16x64_i8 v[84:87], v[144:147], v[188:191], v[84:87]
	s_nop 0
	v_mfma_i32_16x16x64_i8 v[84:87], v[148:151], v[192:195], v[84:87]
	v_mfma_i32_16x16x64_i8 v[80:83], v[152:155], v[188:191], v[80:83]
	s_nop 0
	v_mfma_i32_16x16x64_i8 v[80:83], v[156:159], v[192:195], v[80:83]
	v_mfma_i32_16x16x64_i8 v[68:71], v[144:147], v[196:199], v[68:71]
	s_nop 0
	v_mfma_i32_16x16x64_i8 v[68:71], v[148:151], v[200:203], v[68:71]
	v_mfma_i32_16x16x64_i8 v[64:67], v[152:155], v[196:199], v[64:67]
	s_nop 0
	v_mfma_i32_16x16x64_i8 v[64:67], v[156:159], v[200:203], v[64:67]
	s_setprio 0
	s_barrier
	s_add_u32 s38, s42, 0x80
	s_addc_u32 s39, s43, 0
	ds_read_b128 v[172:175], v168 offset:49152
	ds_read_b128 v[176:179], v168 offset:50176
	ds_read_b128 v[180:183], v168 offset:51200
	ds_read_b128 v[184:187], v168 offset:52224
	ds_read_b128 v[188:191], v168 offset:53248
	ds_read_b128 v[192:195], v168 offset:54272
	ds_read_b128 v[196:199], v168 offset:55296
	ds_read_b128 v[200:203], v168 offset:56320
	s_add_i32 m0, s1, 0x18000
	s_nop 0
	global_load_lds_dwordx4 v164, s[38:39]
	s_nop 0
	s_add_i32 m0, s1, 0x1a000
	s_nop 0
	global_load_lds_dwordx4 v165, s[38:39]
	s_add_u32 s38, s42, 0x80080
	s_addc_u32 s39, s43, 0
	s_add_i32 m0, s1, 0x1c000
	s_nop 0
	global_load_lds_dwordx4 v164, s[38:39]
	s_nop 0
	s_add_i32 m0, s1, 0x1e000
	s_nop 0
	global_load_lds_dwordx4 v165, s[38:39]
	s_nop 0
	s_add_i32 m0, s1, 0x8000
	s_nop 0
	global_load_lds_dwordx4 v164, s[40:41]
	s_nop 0
	s_add_i32 m0, s1, 0xa000
	s_nop 0
	global_load_lds_dwordx4 v165, s[40:41]
	s_waitcnt vmcnt(8)
	s_waitcnt lgkmcnt(0)
	s_barrier
	s_setprio 1
	v_mfma_i32_16x16x64_i8 v[60:63], v[128:131], v[172:175], v[60:63]
	v_mfma_i32_16x16x64_i8 v[60:63], v[132:135], v[176:179], v[60:63]
	v_mfma_i32_16x16x64_i8 v[56:59], v[136:139], v[172:175], v[56:59]
	s_nop 0
	v_mfma_i32_16x16x64_i8 v[56:59], v[140:143], v[176:179], v[56:59]
	v_mfma_i32_16x16x64_i8 v[44:47], v[128:131], v[180:183], v[44:47]
	v_mfma_i32_16x16x64_i8 v[44:47], v[132:135], v[184:187], v[44:47]
	v_mfma_i32_16x16x64_i8 v[40:43], v[136:139], v[180:183], v[40:43]
	s_nop 0
	v_mfma_i32_16x16x64_i8 v[40:43], v[140:143], v[184:187], v[40:43]
	v_mfma_i32_16x16x64_i8 v[28:31], v[128:131], v[188:191], v[28:31]
	v_mfma_i32_16x16x64_i8 v[28:31], v[132:135], v[192:195], v[28:31]
	v_mfma_i32_16x16x64_i8 v[24:27], v[136:139], v[188:191], v[24:27]
	s_nop 0
	v_mfma_i32_16x16x64_i8 v[24:27], v[140:143], v[192:195], v[24:27]
	v_mfma_i32_16x16x64_i8 v[12:15], v[128:131], v[196:199], v[12:15]
	v_mfma_i32_16x16x64_i8 v[12:15], v[132:135], v[200:203], v[12:15]
	v_mfma_i32_16x16x64_i8 v[8:11], v[136:139], v[196:199], v[8:11]
	s_nop 0
	v_mfma_i32_16x16x64_i8 v[8:11], v[140:143], v[200:203], v[8:11]
	v_mfma_i32_16x16x64_i8 v[52:55], v[144:147], v[172:175], v[52:55]
	s_nop 0
	v_mfma_i32_16x16x64_i8 v[52:55], v[148:151], v[176:179], v[52:55]
	v_mfma_i32_16x16x64_i8 v[48:51], v[152:155], v[172:175], v[48:51]
	s_nop 0
	v_mfma_i32_16x16x64_i8 v[48:51], v[156:159], v[176:179], v[48:51]
	v_mfma_i32_16x16x64_i8 v[36:39], v[144:147], v[180:183], v[36:39]
	s_nop 0
	v_mfma_i32_16x16x64_i8 v[36:39], v[148:151], v[184:187], v[36:39]
	v_mfma_i32_16x16x64_i8 v[32:35], v[152:155], v[180:183], v[32:35]
	s_nop 0
	v_mfma_i32_16x16x64_i8 v[32:35], v[156:159], v[184:187], v[32:35]
	v_mfma_i32_16x16x64_i8 v[20:23], v[144:147], v[188:191], v[20:23]
	s_nop 0
	v_mfma_i32_16x16x64_i8 v[20:23], v[148:151], v[192:195], v[20:23]
	v_mfma_i32_16x16x64_i8 v[16:19], v[152:155], v[188:191], v[16:19]
	s_nop 0
	v_mfma_i32_16x16x64_i8 v[16:19], v[156:159], v[192:195], v[16:19]
	v_mfma_i32_16x16x64_i8 v[4:7], v[144:147], v[196:199], v[4:7]
	s_nop 0
	v_mfma_i32_16x16x64_i8 v[4:7], v[148:151], v[200:203], v[4:7]
	v_mfma_i32_16x16x64_i8 v[0:3], v[152:155], v[196:199], v[0:3]
	s_nop 0
	v_mfma_i32_16x16x64_i8 v[0:3], v[156:159], v[200:203], v[0:3]
	s_setprio 0
	s_barrier
	s_add_i32 s62, s62, 2
	s_add_u32 s60, s60, 0x100
	s_addc_u32 s61, s61, 0
	s_cmp_gt_u32 s62, 29
	s_mov_b64 s[38:39], s[36:37]
	s_cbranch_scc0 .LBB0_339
	s_and_b64 vcc, exec, s[14:15]
	s_cbranch_vccz .LBB0_342
	s_barrier

.LBB0_1342:
	ds_read_b128 v[16:19], v216
	ds_read_b128 v[24:27], v216 offset:2048
	ds_read_b128 v[20:23], v217
	ds_read_b128 v[28:31], v217 offset:2048
	ds_read_b128 v[0:3], v218
	ds_read_b128 v[8:11], v218 offset:2048
	ds_read_b128 v[4:7], v219
	ds_read_b128 v[12:15], v219 offset:2048
	s_add_u32 s30, s28, 0x100
	s_addc_u32 s31, s29, 0
	s_cmp_eq_u32 s53, 12
	s_cselect_b32 s38, s23, s30
	s_cselect_b32 s39, s5, s31
	s_cselect_b32 s36, s50, s51
	s_cselect_b32 s37, s21, s52
	s_add_u32 s34, s38, 0x80
	s_addc_u32 s35, s39, 0
	ds_read_b128 v[164:167], v220
	ds_read_b128 v[172:175], v220 offset:2048
	ds_read_b128 v[168:171], v221
	ds_read_b128 v[176:179], v221 offset:2048
	ds_read_b128 v[180:183], v220 offset:4096
	ds_read_b128 v[188:191], v220 offset:6144
	ds_read_b128 v[184:187], v221 offset:4096
	ds_read_b128 v[192:195], v221 offset:6144
	s_add_u32 s28, s28, 0x40080
	s_addc_u32 s29, s29, 0
	s_add_i32 m0, s1, 0xc000
	s_nop 0
	global_load_lds_dwordx4 v211, s[28:29]
	s_nop 0
	s_add_i32 m0, s1, 0xe000
	s_nop 0
	global_load_lds_dwordx4 v212, s[28:29]
	s_waitcnt vmcnt(8)
	s_waitcnt lgkmcnt(0)
	s_barrier
	s_setprio 1
	v_mfma_scale_f32_16x16x128_f8f6f4 v[156:159], v[16:23], v[164:171], v[156:159], v213, v213 op_sel_hi:[0,0,0]
	v_mfma_scale_f32_16x16x128_f8f6f4 v[148:151], v[24:31], v[164:171], v[148:151], v213, v213 op_sel_hi:[0,0,0]
	v_mfma_scale_f32_16x16x128_f8f6f4 v[140:143], v[16:23], v[172:179], v[140:143], v213, v213 op_sel_hi:[0,0,0]
	v_mfma_scale_f32_16x16x128_f8f6f4 v[132:135], v[24:31], v[172:179], v[132:135], v213, v213 op_sel_hi:[0,0,0]
	v_mfma_scale_f32_16x16x128_f8f6f4 v[124:127], v[16:23], v[180:187], v[124:127], v213, v213 op_sel_hi:[0,0,0]
	v_mfma_scale_f32_16x16x128_f8f6f4 v[116:119], v[24:31], v[180:187], v[116:119], v213, v213 op_sel_hi:[0,0,0]
	v_mfma_scale_f32_16x16x128_f8f6f4 v[108:111], v[16:23], v[188:195], v[108:111], v213, v213 op_sel_hi:[0,0,0]
	v_mfma_scale_f32_16x16x128_f8f6f4 v[100:103], v[24:31], v[188:195], v[100:103], v213, v213 op_sel_hi:[0,0,0]
	v_mfma_scale_f32_16x16x128_f8f6f4 v[152:155], v[0:7], v[164:171], v[152:155], v213, v213 op_sel_hi:[0,0,0]
	v_mfma_scale_f32_16x16x128_f8f6f4 v[144:147], v[8:15], v[164:171], v[144:147], v213, v213 op_sel_hi:[0,0,0]
	v_mfma_scale_f32_16x16x128_f8f6f4 v[136:139], v[0:7], v[172:179], v[136:139], v213, v213 op_sel_hi:[0,0,0]
	v_mfma_scale_f32_16x16x128_f8f6f4 v[128:131], v[8:15], v[172:179], v[128:131], v213, v213 op_sel_hi:[0,0,0]
	v_mfma_scale_f32_16x16x128_f8f6f4 v[120:123], v[0:7], v[180:187], v[120:123], v213, v213 op_sel_hi:[0,0,0]
	v_mfma_scale_f32_16x16x128_f8f6f4 v[112:115], v[8:15], v[180:187], v[112:115], v213, v213 op_sel_hi:[0,0,0]
	v_mfma_scale_f32_16x16x128_f8f6f4 v[104:107], v[0:7], v[188:195], v[104:107], v213, v213 op_sel_hi:[0,0,0]
	v_mfma_scale_f32_16x16x128_f8f6f4 v[96:99], v[8:15], v[188:195], v[96:99], v213, v213 op_sel_hi:[0,0,0]
	s_setprio 0
	s_barrier
	ds_read_b128 v[164:167], v220 offset:16384
	ds_read_b128 v[172:175], v220 offset:18432
	ds_read_b128 v[168:171], v221 offset:16384
	ds_read_b128 v[176:179], v221 offset:18432
	ds_read_b128 v[180:183], v220 offset:20480
	ds_read_b128 v[188:191], v220 offset:22528
	ds_read_b128 v[184:187], v221 offset:20480
	ds_read_b128 v[192:195], v221 offset:22528
	s_add_i32 m0, s1, 0x10000
	s_nop 0
	global_load_lds_dwordx4 v211, s[36:37]
	s_nop 0
	s_add_i32 m0, s1, 0x12000
	s_nop 0
	global_load_lds_dwordx4 v212, s[36:37]
	s_add_u32 s28, s36, 0x40000
	s_addc_u32 s29, s37, 0
	s_add_i32 m0, s1, 0x14000
	s_nop 0
	global_load_lds_dwordx4 v211, s[28:29]
	s_nop 0
	s_add_i32 m0, s1, 0x16000
	s_nop 0
	global_load_lds_dwordx4 v212, s[28:29]
	s_nop 0
	s_add_i32 m0, s1, 0
	s_nop 0
	global_load_lds_dwordx4 v211, s[38:39]
	s_nop 0
	s_add_i32 m0, s1, 0x2000
	s_nop 0
	global_load_lds_dwordx4 v212, s[38:39]
	s_waitcnt vmcnt(8)
	s_waitcnt lgkmcnt(0)
	s_barrier
	s_setprio 1
	v_mfma_scale_f32_16x16x128_f8f6f4 v[92:95], v[16:23], v[164:171], v[92:95], v213, v213 op_sel_hi:[0,0,0]
	v_mfma_scale_f32_16x16x128_f8f6f4 v[84:87], v[24:31], v[164:171], v[84:87], v213, v213 op_sel_hi:[0,0,0]
	v_mfma_scale_f32_16x16x128_f8f6f4 v[76:79], v[16:23], v[172:179], v[76:79], v213, v213 op_sel_hi:[0,0,0]
	v_mfma_scale_f32_16x16x128_f8f6f4 v[68:71], v[24:31], v[172:179], v[68:71], v213, v213 op_sel_hi:[0,0,0]
	v_mfma_scale_f32_16x16x128_f8f6f4 v[60:63], v[16:23], v[180:187], v[60:63], v213, v213 op_sel_hi:[0,0,0]
	v_mfma_scale_f32_16x16x128_f8f6f4 v[52:55], v[24:31], v[180:187], v[52:55], v213, v213 op_sel_hi:[0,0,0]
	v_mfma_scale_f32_16x16x128_f8f6f4 v[44:47], v[16:23], v[188:195], v[44:47], v213, v213 op_sel_hi:[0,0,0]
	v_mfma_scale_f32_16x16x128_f8f6f4 v[36:39], v[24:31], v[188:195], v[36:39], v213, v213 op_sel_hi:[0,0,0]
	v_mfma_scale_f32_16x16x128_f8f6f4 v[88:91], v[0:7], v[164:171], v[88:91], v213, v213 op_sel_hi:[0,0,0]
	v_mfma_scale_f32_16x16x128_f8f6f4 v[80:83], v[8:15], v[164:171], v[80:83], v213, v213 op_sel_hi:[0,0,0]
	v_mfma_scale_f32_16x16x128_f8f6f4 v[72:75], v[0:7], v[172:179], v[72:75], v213, v213 op_sel_hi:[0,0,0]
	v_mfma_scale_f32_16x16x128_f8f6f4 v[64:67], v[8:15], v[172:179], v[64:67], v213, v213 op_sel_hi:[0,0,0]
	v_mfma_scale_f32_16x16x128_f8f6f4 v[56:59], v[0:7], v[180:187], v[56:59], v213, v213 op_sel_hi:[0,0,0]
	v_mfma_scale_f32_16x16x128_f8f6f4 v[48:51], v[8:15], v[180:187], v[48:51], v213, v213 op_sel_hi:[0,0,0]
	v_mfma_scale_f32_16x16x128_f8f6f4 v[40:43], v[0:7], v[188:195], v[40:43], v213, v213 op_sel_hi:[0,0,0]
	v_mfma_scale_f32_16x16x128_f8f6f4 v[32:35], v[8:15], v[188:195], v[32:35], v213, v213 op_sel_hi:[0,0,0]
	s_setprio 0
	s_barrier
	ds_read_b128 v[0:3], v222
	ds_read_b128 v[8:11], v222 offset:2048
	ds_read_b128 v[4:7], v225
	ds_read_b128 v[12:15], v225 offset:2048
	ds_read_b128 v[16:19], v226
	ds_read_b128 v[24:27], v226 offset:2048
	ds_read_b128 v[20:23], v227
	ds_read_b128 v[28:31], v227 offset:2048
	ds_read_b128 v[164:167], v220 offset:32768
	ds_read_b128 v[172:175], v220 offset:34816
	ds_read_b128 v[168:171], v221 offset:32768
	ds_read_b128 v[176:179], v221 offset:34816
	ds_read_b128 v[180:183], v220 offset:36864
	ds_read_b128 v[188:191], v220 offset:38912
	ds_read_b128 v[184:187], v221 offset:36864
	ds_read_b128 v[192:195], v221 offset:38912
	s_add_u32 s28, s38, 0x40000
	s_addc_u32 s29, s39, 0
	s_add_i32 m0, s1, 0x4000
	s_nop 0
	global_load_lds_dwordx4 v211, s[28:29]
	s_nop 0
	s_add_i32 m0, s1, 0x6000
	s_nop 0
	global_load_lds_dwordx4 v212, s[28:29]
	s_waitcnt vmcnt(8)
	s_waitcnt lgkmcnt(0)
	s_barrier
	s_setprio 1
	v_mfma_scale_f32_16x16x128_f8f6f4 v[156:159], v[0:7], v[164:171], v[156:159], v213, v213 op_sel_hi:[0,0,0]
	v_mfma_scale_f32_16x16x128_f8f6f4 v[148:151], v[8:15], v[164:171], v[148:151], v213, v213 op_sel_hi:[0,0,0]
	v_mfma_scale_f32_16x16x128_f8f6f4 v[140:143], v[0:7], v[172:179], v[140:143], v213, v213 op_sel_hi:[0,0,0]
	v_mfma_scale_f32_16x16x128_f8f6f4 v[132:135], v[8:15], v[172:179], v[132:135], v213, v213 op_sel_hi:[0,0,0]
	v_mfma_scale_f32_16x16x128_f8f6f4 v[124:127], v[0:7], v[180:187], v[124:127], v213, v213 op_sel_hi:[0,0,0]
	v_mfma_scale_f32_16x16x128_f8f6f4 v[116:119], v[8:15], v[180:187], v[116:119], v213, v213 op_sel_hi:[0,0,0]
	v_mfma_scale_f32_16x16x128_f8f6f4 v[108:111], v[0:7], v[188:195], v[108:111], v213, v213 op_sel_hi:[0,0,0]
	v_mfma_scale_f32_16x16x128_f8f6f4 v[100:103], v[8:15], v[188:195], v[100:103], v213, v213 op_sel_hi:[0,0,0]
	v_mfma_scale_f32_16x16x128_f8f6f4 v[152:155], v[16:23], v[164:171], v[152:155], v213, v213 op_sel_hi:[0,0,0]
	v_mfma_scale_f32_16x16x128_f8f6f4 v[144:147], v[24:31], v[164:171], v[144:147], v213, v213 op_sel_hi:[0,0,0]
	v_mfma_scale_f32_16x16x128_f8f6f4 v[136:139], v[16:23], v[172:179], v[136:139], v213, v213 op_sel_hi:[0,0,0]
	v_mfma_scale_f32_16x16x128_f8f6f4 v[128:131], v[24:31], v[172:179], v[128:131], v213, v213 op_sel_hi:[0,0,0]
	v_mfma_scale_f32_16x16x128_f8f6f4 v[120:123], v[16:23], v[180:187], v[120:123], v213, v213 op_sel_hi:[0,0,0]
	v_mfma_scale_f32_16x16x128_f8f6f4 v[112:115], v[24:31], v[180:187], v[112:115], v213, v213 op_sel_hi:[0,0,0]
	v_mfma_scale_f32_16x16x128_f8f6f4 v[104:107], v[16:23], v[188:195], v[104:107], v213, v213 op_sel_hi:[0,0,0]
	v_mfma_scale_f32_16x16x128_f8f6f4 v[96:99], v[24:31], v[188:195], v[96:99], v213, v213 op_sel_hi:[0,0,0]
	s_setprio 0
	s_barrier
	s_add_u32 s28, s36, 0x80
	ds_read_b128 v[164:167], v220 offset:49152
	ds_read_b128 v[172:175], v220 offset:51200
	ds_read_b128 v[168:171], v221 offset:49152
	ds_read_b128 v[176:179], v221 offset:51200
	ds_read_b128 v[180:183], v220 offset:53248
	ds_read_b128 v[188:191], v220 offset:55296
	ds_read_b128 v[184:187], v221 offset:53248
	ds_read_b128 v[192:195], v221 offset:55296
	s_addc_u32 s29, s37, 0
	s_add_i32 m0, s1, 0x18000
	s_nop 0
	global_load_lds_dwordx4 v211, s[28:29]
	s_nop 0
	s_add_i32 m0, s1, 0x1a000
	s_nop 0
	global_load_lds_dwordx4 v212, s[28:29]
	s_add_u32 s28, s36, 0x40080
	s_addc_u32 s29, s37, 0
	s_add_i32 m0, s1, 0x1c000
	s_nop 0
	global_load_lds_dwordx4 v211, s[28:29]
	s_nop 0
	s_add_i32 m0, s1, 0x1e000
	s_nop 0
	global_load_lds_dwordx4 v212, s[28:29]
	s_nop 0
	s_add_i32 m0, s1, 0x8000
	s_nop 0
	global_load_lds_dwordx4 v211, s[34:35]
	s_nop 0
	s_add_i32 m0, s1, 0xa000
	s_nop 0
	global_load_lds_dwordx4 v212, s[34:35]
	s_waitcnt vmcnt(8)
	s_waitcnt lgkmcnt(0)
	s_barrier
	s_setprio 1
	v_mfma_scale_f32_16x16x128_f8f6f4 v[92:95], v[0:7], v[164:171], v[92:95], v213, v213 op_sel_hi:[0,0,0]
	v_mfma_scale_f32_16x16x128_f8f6f4 v[84:87], v[8:15], v[164:171], v[84:87], v213, v213 op_sel_hi:[0,0,0]
	v_mfma_scale_f32_16x16x128_f8f6f4 v[76:79], v[0:7], v[172:179], v[76:79], v213, v213 op_sel_hi:[0,0,0]
	v_mfma_scale_f32_16x16x128_f8f6f4 v[68:71], v[8:15], v[172:179], v[68:71], v213, v213 op_sel_hi:[0,0,0]
	v_mfma_scale_f32_16x16x128_f8f6f4 v[60:63], v[0:7], v[180:187], v[60:63], v213, v213 op_sel_hi:[0,0,0]
	v_mfma_scale_f32_16x16x128_f8f6f4 v[52:55], v[8:15], v[180:187], v[52:55], v213, v213 op_sel_hi:[0,0,0]
	v_mfma_scale_f32_16x16x128_f8f6f4 v[44:47], v[0:7], v[188:195], v[44:47], v213, v213 op_sel_hi:[0,0,0]
	v_mfma_scale_f32_16x16x128_f8f6f4 v[36:39], v[8:15], v[188:195], v[36:39], v213, v213 op_sel_hi:[0,0,0]
	v_mfma_scale_f32_16x16x128_f8f6f4 v[88:91], v[16:23], v[164:171], v[88:91], v213, v213 op_sel_hi:[0,0,0]
	v_mfma_scale_f32_16x16x128_f8f6f4 v[80:83], v[24:31], v[164:171], v[80:83], v213, v213 op_sel_hi:[0,0,0]
	v_mfma_scale_f32_16x16x128_f8f6f4 v[72:75], v[16:23], v[172:179], v[72:75], v213, v213 op_sel_hi:[0,0,0]
	v_mfma_scale_f32_16x16x128_f8f6f4 v[64:67], v[24:31], v[172:179], v[64:67], v213, v213 op_sel_hi:[0,0,0]
	v_mfma_scale_f32_16x16x128_f8f6f4 v[56:59], v[16:23], v[180:187], v[56:59], v213, v213 op_sel_hi:[0,0,0]
	v_mfma_scale_f32_16x16x128_f8f6f4 v[48:51], v[24:31], v[180:187], v[48:51], v213, v213 op_sel_hi:[0,0,0]
	v_mfma_scale_f32_16x16x128_f8f6f4 v[40:43], v[16:23], v[188:195], v[40:43], v213, v213 op_sel_hi:[0,0,0]
	v_mfma_scale_f32_16x16x128_f8f6f4 v[32:35], v[24:31], v[188:195], v[32:35], v213, v213 op_sel_hi:[0,0,0]
	s_setprio 0
	s_barrier
	s_add_i32 s53, s53, 2
	s_add_u32 s51, s51, 0x100
	s_addc_u32 s52, s52, 0
	s_cmp_gt_u32 s53, 13
	s_mov_b64 s[28:29], s[30:31]
	s_cbranch_scc0 .LBB0_1342
	s_and_b64 vcc, exec, s[16:17]
	s_cbranch_vccz .LBB0_1345
	s_barrier

.LBB0_1493:
	ds_read_b128 v[156:159], v229
	ds_read_b128 v[152:155], v229 offset:1024
	ds_read_b128 v[148:151], v229 offset:2048
	ds_read_b128 v[144:147], v229 offset:3072
	ds_read_b128 v[140:143], v230
	ds_read_b128 v[136:139], v230 offset:1024
	ds_read_b128 v[132:135], v230 offset:2048
	ds_read_b128 v[128:131], v230 offset:3072
	s_add_u32 s38, s40, 0x100
	s_addc_u32 s39, s41, 0
	s_cmp_eq_u32 s60, 28
	s_cselect_b32 s46, s37, s38
	s_cselect_b32 s47, s29, s39
	s_cselect_b32 s44, s57, s58
	s_cselect_b32 s45, s27, s59
	s_add_u32 s42, s46, 0x80
	s_addc_u32 s43, s47, 0
	ds_read_b128 v[160:163], v231
	ds_read_b128 v[164:167], v231 offset:1024
	ds_read_b128 v[168:171], v231 offset:2048
	ds_read_b128 v[172:175], v231 offset:3072
	ds_read_b128 v[176:179], v231 offset:4096
	ds_read_b128 v[180:183], v231 offset:5120
	ds_read_b128 v[184:187], v231 offset:6144
	ds_read_b128 v[192:195], v231 offset:7168
	s_add_u32 s40, s40, 0x80080
	s_addc_u32 s41, s41, 0
	s_add_i32 m0, s1, 0xc000
	s_nop 0
	global_load_lds_dwordx4 v225, s[40:41]
	s_nop 0
	s_add_i32 m0, s1, 0xe000
	s_nop 0
	global_load_lds_dwordx4 v226, s[40:41]
	s_waitcnt vmcnt(8)
	s_waitcnt lgkmcnt(0)
	s_barrier
	s_setprio 1
	v_mfma_i32_16x16x64_i8 v[124:127], v[156:159], v[160:163], v[124:127]
	v_mfma_i32_16x16x64_i8 v[124:127], v[152:155], v[164:167], v[124:127]
	v_mfma_i32_16x16x64_i8 v[120:123], v[148:151], v[160:163], v[120:123]
	s_nop 0
	v_mfma_i32_16x16x64_i8 v[120:123], v[144:147], v[164:167], v[120:123]
	v_mfma_i32_16x16x64_i8 v[108:111], v[156:159], v[168:171], v[108:111]
	v_mfma_i32_16x16x64_i8 v[108:111], v[152:155], v[172:175], v[108:111]
	v_mfma_i32_16x16x64_i8 v[104:107], v[148:151], v[168:171], v[104:107]
	s_nop 0
	v_mfma_i32_16x16x64_i8 v[104:107], v[144:147], v[172:175], v[104:107]
	v_mfma_i32_16x16x64_i8 v[92:95], v[156:159], v[176:179], v[92:95]
	v_mfma_i32_16x16x64_i8 v[92:95], v[152:155], v[180:183], v[92:95]
	v_mfma_i32_16x16x64_i8 v[88:91], v[148:151], v[176:179], v[88:91]
	s_nop 0
	v_mfma_i32_16x16x64_i8 v[88:91], v[144:147], v[180:183], v[88:91]
	v_mfma_i32_16x16x64_i8 v[76:79], v[156:159], v[184:187], v[76:79]
	v_mfma_i32_16x16x64_i8 v[76:79], v[152:155], v[192:195], v[76:79]
	v_mfma_i32_16x16x64_i8 v[72:75], v[148:151], v[184:187], v[72:75]
	s_nop 0
	v_mfma_i32_16x16x64_i8 v[72:75], v[144:147], v[192:195], v[72:75]
	v_mfma_i32_16x16x64_i8 v[116:119], v[140:143], v[160:163], v[116:119]
	s_nop 0
	v_mfma_i32_16x16x64_i8 v[116:119], v[136:139], v[164:167], v[116:119]
	v_mfma_i32_16x16x64_i8 v[112:115], v[132:135], v[160:163], v[112:115]
	s_nop 0
	v_mfma_i32_16x16x64_i8 v[112:115], v[128:131], v[164:167], v[112:115]
	v_mfma_i32_16x16x64_i8 v[100:103], v[140:143], v[168:171], v[100:103]
	s_nop 0
	v_mfma_i32_16x16x64_i8 v[100:103], v[136:139], v[172:175], v[100:103]
	v_mfma_i32_16x16x64_i8 v[96:99], v[132:135], v[168:171], v[96:99]
	s_nop 0
	v_mfma_i32_16x16x64_i8 v[96:99], v[128:131], v[172:175], v[96:99]
	v_mfma_i32_16x16x64_i8 v[84:87], v[140:143], v[176:179], v[84:87]
	s_nop 0
	v_mfma_i32_16x16x64_i8 v[84:87], v[136:139], v[180:183], v[84:87]
	v_mfma_i32_16x16x64_i8 v[80:83], v[132:135], v[176:179], v[80:83]
	s_nop 0
	v_mfma_i32_16x16x64_i8 v[80:83], v[128:131], v[180:183], v[80:83]
	v_mfma_i32_16x16x64_i8 v[68:71], v[140:143], v[184:187], v[68:71]
	s_nop 0
	v_mfma_i32_16x16x64_i8 v[68:71], v[136:139], v[192:195], v[68:71]
	v_mfma_i32_16x16x64_i8 v[64:67], v[132:135], v[184:187], v[64:67]
	s_nop 0
	v_mfma_i32_16x16x64_i8 v[64:67], v[128:131], v[192:195], v[64:67]
	s_setprio 0
	s_barrier
	ds_read_b128 v[160:163], v231 offset:16384
	ds_read_b128 v[164:167], v231 offset:17408
	ds_read_b128 v[168:171], v231 offset:18432
	ds_read_b128 v[172:175], v231 offset:19456
	ds_read_b128 v[176:179], v231 offset:20480
	ds_read_b128 v[180:183], v231 offset:21504
	ds_read_b128 v[184:187], v231 offset:22528
	ds_read_b128 v[192:195], v231 offset:23552
	s_add_i32 m0, s1, 0x10000
	s_nop 0
	global_load_lds_dwordx4 v225, s[44:45]
	s_nop 0
	s_add_i32 m0, s1, 0x12000
	s_nop 0
	global_load_lds_dwordx4 v226, s[44:45]
	s_add_u32 s40, s44, 0x80000
	s_addc_u32 s41, s45, 0
	s_add_i32 m0, s1, 0x14000
	s_nop 0
	global_load_lds_dwordx4 v225, s[40:41]
	s_nop 0
	s_add_i32 m0, s1, 0x16000
	s_nop 0
	global_load_lds_dwordx4 v226, s[40:41]
	s_nop 0
	s_add_i32 m0, s1, 0
	s_nop 0
	global_load_lds_dwordx4 v225, s[46:47]
	s_nop 0
	s_add_i32 m0, s1, 0x2000
	s_nop 0
	global_load_lds_dwordx4 v226, s[46:47]
	s_waitcnt vmcnt(8)
	s_waitcnt lgkmcnt(0)
	s_barrier
	s_setprio 1
	v_mfma_i32_16x16x64_i8 v[60:63], v[156:159], v[160:163], v[60:63]
	v_mfma_i32_16x16x64_i8 v[60:63], v[152:155], v[164:167], v[60:63]
	v_mfma_i32_16x16x64_i8 v[56:59], v[148:151], v[160:163], v[56:59]
	s_nop 0
	v_mfma_i32_16x16x64_i8 v[56:59], v[144:147], v[164:167], v[56:59]
	v_mfma_i32_16x16x64_i8 v[44:47], v[156:159], v[168:171], v[44:47]
	v_mfma_i32_16x16x64_i8 v[44:47], v[152:155], v[172:175], v[44:47]
	v_mfma_i32_16x16x64_i8 v[40:43], v[148:151], v[168:171], v[40:43]
	s_nop 0
	v_mfma_i32_16x16x64_i8 v[40:43], v[144:147], v[172:175], v[40:43]
	v_mfma_i32_16x16x64_i8 v[28:31], v[156:159], v[176:179], v[28:31]
	v_mfma_i32_16x16x64_i8 v[28:31], v[152:155], v[180:183], v[28:31]
	v_mfma_i32_16x16x64_i8 v[24:27], v[148:151], v[176:179], v[24:27]
	s_nop 0
	v_mfma_i32_16x16x64_i8 v[24:27], v[144:147], v[180:183], v[24:27]
	v_mfma_i32_16x16x64_i8 v[12:15], v[156:159], v[184:187], v[12:15]
	v_mfma_i32_16x16x64_i8 v[12:15], v[152:155], v[192:195], v[12:15]
	v_mfma_i32_16x16x64_i8 v[8:11], v[148:151], v[184:187], v[8:11]
	s_nop 0
	v_mfma_i32_16x16x64_i8 v[8:11], v[144:147], v[192:195], v[8:11]
	v_mfma_i32_16x16x64_i8 v[52:55], v[140:143], v[160:163], v[52:55]
	s_nop 0
	v_mfma_i32_16x16x64_i8 v[52:55], v[136:139], v[164:167], v[52:55]
	v_mfma_i32_16x16x64_i8 v[48:51], v[132:135], v[160:163], v[48:51]
	s_nop 0
	v_mfma_i32_16x16x64_i8 v[48:51], v[128:131], v[164:167], v[48:51]
	v_mfma_i32_16x16x64_i8 v[36:39], v[140:143], v[168:171], v[36:39]
	s_nop 0
	v_mfma_i32_16x16x64_i8 v[36:39], v[136:139], v[172:175], v[36:39]
	v_mfma_i32_16x16x64_i8 v[32:35], v[132:135], v[168:171], v[32:35]
	s_nop 0
	v_mfma_i32_16x16x64_i8 v[32:35], v[128:131], v[172:175], v[32:35]
	v_mfma_i32_16x16x64_i8 v[20:23], v[140:143], v[176:179], v[20:23]
	s_nop 0
	v_mfma_i32_16x16x64_i8 v[20:23], v[136:139], v[180:183], v[20:23]
	v_mfma_i32_16x16x64_i8 v[16:19], v[132:135], v[176:179], v[16:19]
	s_nop 0
	v_mfma_i32_16x16x64_i8 v[16:19], v[128:131], v[180:183], v[16:19]
	v_mfma_i32_16x16x64_i8 v[4:7], v[140:143], v[184:187], v[4:7]
	s_nop 0
	v_mfma_i32_16x16x64_i8 v[4:7], v[136:139], v[192:195], v[4:7]
	v_mfma_i32_16x16x64_i8 v[0:3], v[132:135], v[184:187], v[0:3]
	s_nop 0
	v_mfma_i32_16x16x64_i8 v[0:3], v[128:131], v[192:195], v[0:3]
	s_setprio 0
	s_barrier
	ds_read_b128 v[128:131], v232
	ds_read_b128 v[132:135], v232 offset:1024
	ds_read_b128 v[136:139], v232 offset:2048
	ds_read_b128 v[140:143], v232 offset:3072
	ds_read_b128 v[144:147], v233
	ds_read_b128 v[148:151], v233 offset:1024
	ds_read_b128 v[152:155], v233 offset:2048
	ds_read_b128 v[156:159], v233 offset:3072
	ds_read_b128 v[160:163], v231 offset:32768
	ds_read_b128 v[164:167], v231 offset:33792
	ds_read_b128 v[168:171], v231 offset:34816
	ds_read_b128 v[172:175], v231 offset:35840
	ds_read_b128 v[176:179], v231 offset:36864
	ds_read_b128 v[180:183], v231 offset:37888
	ds_read_b128 v[184:187], v231 offset:38912
	ds_read_b128 v[192:195], v231 offset:39936
	s_add_u32 s40, s46, 0x80000
	s_addc_u32 s41, s47, 0
	s_add_i32 m0, s1, 0x4000
	s_nop 0
	global_load_lds_dwordx4 v225, s[40:41]
	s_nop 0
	s_add_i32 m0, s1, 0x6000
	s_nop 0
	global_load_lds_dwordx4 v226, s[40:41]
	s_waitcnt vmcnt(8)
	s_waitcnt lgkmcnt(0)
	s_barrier
	s_setprio 1
	v_mfma_i32_16x16x64_i8 v[124:127], v[128:131], v[160:163], v[124:127]
	v_mfma_i32_16x16x64_i8 v[124:127], v[132:135], v[164:167], v[124:127]
	v_mfma_i32_16x16x64_i8 v[120:123], v[136:139], v[160:163], v[120:123]
	s_nop 0
	v_mfma_i32_16x16x64_i8 v[120:123], v[140:143], v[164:167], v[120:123]
	v_mfma_i32_16x16x64_i8 v[108:111], v[128:131], v[168:171], v[108:111]
	v_mfma_i32_16x16x64_i8 v[108:111], v[132:135], v[172:175], v[108:111]
	v_mfma_i32_16x16x64_i8 v[104:107], v[136:139], v[168:171], v[104:107]
	s_nop 0
	v_mfma_i32_16x16x64_i8 v[104:107], v[140:143], v[172:175], v[104:107]
	v_mfma_i32_16x16x64_i8 v[92:95], v[128:131], v[176:179], v[92:95]
	v_mfma_i32_16x16x64_i8 v[92:95], v[132:135], v[180:183], v[92:95]
	v_mfma_i32_16x16x64_i8 v[88:91], v[136:139], v[176:179], v[88:91]
	s_nop 0
	v_mfma_i32_16x16x64_i8 v[88:91], v[140:143], v[180:183], v[88:91]
	v_mfma_i32_16x16x64_i8 v[76:79], v[128:131], v[184:187], v[76:79]
	v_mfma_i32_16x16x64_i8 v[76:79], v[132:135], v[192:195], v[76:79]
	v_mfma_i32_16x16x64_i8 v[72:75], v[136:139], v[184:187], v[72:75]
	s_nop 0
	v_mfma_i32_16x16x64_i8 v[72:75], v[140:143], v[192:195], v[72:75]
	v_mfma_i32_16x16x64_i8 v[116:119], v[144:147], v[160:163], v[116:119]
	s_nop 0
	v_mfma_i32_16x16x64_i8 v[116:119], v[148:151], v[164:167], v[116:119]
	v_mfma_i32_16x16x64_i8 v[112:115], v[152:155], v[160:163], v[112:115]
	s_nop 0
	v_mfma_i32_16x16x64_i8 v[112:115], v[156:159], v[164:167], v[112:115]
	v_mfma_i32_16x16x64_i8 v[100:103], v[144:147], v[168:171], v[100:103]
	s_nop 0
	v_mfma_i32_16x16x64_i8 v[100:103], v[148:151], v[172:175], v[100:103]
	v_mfma_i32_16x16x64_i8 v[96:99], v[152:155], v[168:171], v[96:99]
	s_nop 0
	v_mfma_i32_16x16x64_i8 v[96:99], v[156:159], v[172:175], v[96:99]
	v_mfma_i32_16x16x64_i8 v[84:87], v[144:147], v[176:179], v[84:87]
	s_nop 0
	v_mfma_i32_16x16x64_i8 v[84:87], v[148:151], v[180:183], v[84:87]
	v_mfma_i32_16x16x64_i8 v[80:83], v[152:155], v[176:179], v[80:83]
	s_nop 0
	v_mfma_i32_16x16x64_i8 v[80:83], v[156:159], v[180:183], v[80:83]
	v_mfma_i32_16x16x64_i8 v[68:71], v[144:147], v[184:187], v[68:71]
	s_nop 0
	v_mfma_i32_16x16x64_i8 v[68:71], v[148:151], v[192:195], v[68:71]
	v_mfma_i32_16x16x64_i8 v[64:67], v[152:155], v[184:187], v[64:67]
	s_nop 0
	v_mfma_i32_16x16x64_i8 v[64:67], v[156:159], v[192:195], v[64:67]
	s_setprio 0
	s_barrier
	s_add_u32 s40, s44, 0x80
	s_addc_u32 s41, s45, 0
	ds_read_b128 v[160:163], v231 offset:49152
	ds_read_b128 v[164:167], v231 offset:50176
	ds_read_b128 v[168:171], v231 offset:51200
	ds_read_b128 v[172:175], v231 offset:52224
	ds_read_b128 v[176:179], v231 offset:53248
	ds_read_b128 v[180:183], v231 offset:54272
	ds_read_b128 v[184:187], v231 offset:55296
	ds_read_b128 v[192:195], v231 offset:56320
	s_add_i32 m0, s1, 0x18000
	s_nop 0
	global_load_lds_dwordx4 v225, s[40:41]
	s_nop 0
	s_add_i32 m0, s1, 0x1a000
	s_nop 0
	global_load_lds_dwordx4 v226, s[40:41]
	s_add_u32 s40, s44, 0x80080
	s_addc_u32 s41, s45, 0
	s_add_i32 m0, s1, 0x1c000
	s_nop 0
	global_load_lds_dwordx4 v225, s[40:41]
	s_nop 0
	s_add_i32 m0, s1, 0x1e000
	s_nop 0
	global_load_lds_dwordx4 v226, s[40:41]
	s_nop 0
	s_add_i32 m0, s1, 0x8000
	s_nop 0
	global_load_lds_dwordx4 v225, s[42:43]
	s_nop 0
	s_add_i32 m0, s1, 0xa000
	s_nop 0
	global_load_lds_dwordx4 v226, s[42:43]
	s_waitcnt vmcnt(8)
	s_waitcnt lgkmcnt(0)
	s_barrier
	s_setprio 1
	v_mfma_i32_16x16x64_i8 v[60:63], v[128:131], v[160:163], v[60:63]
	v_mfma_i32_16x16x64_i8 v[60:63], v[132:135], v[164:167], v[60:63]
	v_mfma_i32_16x16x64_i8 v[56:59], v[136:139], v[160:163], v[56:59]
	s_nop 0
	v_mfma_i32_16x16x64_i8 v[56:59], v[140:143], v[164:167], v[56:59]
	v_mfma_i32_16x16x64_i8 v[44:47], v[128:131], v[168:171], v[44:47]
	v_mfma_i32_16x16x64_i8 v[44:47], v[132:135], v[172:175], v[44:47]
	v_mfma_i32_16x16x64_i8 v[40:43], v[136:139], v[168:171], v[40:43]
	s_nop 0
	v_mfma_i32_16x16x64_i8 v[40:43], v[140:143], v[172:175], v[40:43]
	v_mfma_i32_16x16x64_i8 v[28:31], v[128:131], v[176:179], v[28:31]
	v_mfma_i32_16x16x64_i8 v[28:31], v[132:135], v[180:183], v[28:31]
	v_mfma_i32_16x16x64_i8 v[24:27], v[136:139], v[176:179], v[24:27]
	s_nop 0
	v_mfma_i32_16x16x64_i8 v[24:27], v[140:143], v[180:183], v[24:27]
	v_mfma_i32_16x16x64_i8 v[12:15], v[128:131], v[184:187], v[12:15]
	v_mfma_i32_16x16x64_i8 v[12:15], v[132:135], v[192:195], v[12:15]
	v_mfma_i32_16x16x64_i8 v[8:11], v[136:139], v[184:187], v[8:11]
	s_nop 0
	v_mfma_i32_16x16x64_i8 v[8:11], v[140:143], v[192:195], v[8:11]
	v_mfma_i32_16x16x64_i8 v[52:55], v[144:147], v[160:163], v[52:55]
	s_nop 0
	v_mfma_i32_16x16x64_i8 v[52:55], v[148:151], v[164:167], v[52:55]
	v_mfma_i32_16x16x64_i8 v[48:51], v[152:155], v[160:163], v[48:51]
	s_nop 0
	v_mfma_i32_16x16x64_i8 v[48:51], v[156:159], v[164:167], v[48:51]
	v_mfma_i32_16x16x64_i8 v[36:39], v[144:147], v[168:171], v[36:39]
	s_nop 0
	v_mfma_i32_16x16x64_i8 v[36:39], v[148:151], v[172:175], v[36:39]
	v_mfma_i32_16x16x64_i8 v[32:35], v[152:155], v[168:171], v[32:35]
	s_nop 0
	v_mfma_i32_16x16x64_i8 v[32:35], v[156:159], v[172:175], v[32:35]
	v_mfma_i32_16x16x64_i8 v[20:23], v[144:147], v[176:179], v[20:23]
	s_nop 0
	v_mfma_i32_16x16x64_i8 v[20:23], v[148:151], v[180:183], v[20:23]
	v_mfma_i32_16x16x64_i8 v[16:19], v[152:155], v[176:179], v[16:19]
	s_nop 0
	v_mfma_i32_16x16x64_i8 v[16:19], v[156:159], v[180:183], v[16:19]
	v_mfma_i32_16x16x64_i8 v[4:7], v[144:147], v[184:187], v[4:7]
	s_nop 0
	v_mfma_i32_16x16x64_i8 v[4:7], v[148:151], v[192:195], v[4:7]
	v_mfma_i32_16x16x64_i8 v[0:3], v[152:155], v[184:187], v[0:3]
	s_nop 0
	v_mfma_i32_16x16x64_i8 v[0:3], v[156:159], v[192:195], v[0:3]
	s_setprio 0
	s_barrier
	s_add_i32 s60, s60, 2
	s_add_u32 s58, s58, 0x100
	s_addc_u32 s59, s59, 0
	s_cmp_gt_u32 s60, 29
	s_mov_b64 s[40:41], s[38:39]
	s_cbranch_scc0 .LBB0_1493
	s_and_b64 vcc, exec, s[20:21]
	s_cbranch_vccz .LBB0_1496
	s_barrier

.LBB0_1605:
	ds_read_b128 v[120:123], v154
	ds_read_b128 v[124:127], v154 offset:1024
	ds_read_b128 v[136:139], v154 offset:2048
	ds_read_b128 v[140:143], v154 offset:3072
	ds_read_b128 v[148:151], v155
	ds_read_b128 v[160:163], v155 offset:1024
	ds_read_b128 v[164:167], v155 offset:2048
	ds_read_b128 v[168:171], v155 offset:3072
	s_add_u32 s36, s34, 0x100
	s_addc_u32 s37, s35, 0
	s_cmp_eq_u32 s62, 60
	s_cselect_b32 s42, s58, s36
	s_cselect_b32 s43, s25, s37
	s_cselect_b32 s40, s59, s60
	s_cselect_b32 s41, s23, s61
	s_add_u32 s38, s42, 0x80
	s_addc_u32 s39, s43, 0
	ds_read_b128 v[172:175], v156
	ds_read_b128 v[176:179], v156 offset:1024
	ds_read_b128 v[180:183], v156 offset:2048
	ds_read_b128 v[184:187], v156 offset:3072
	ds_read_b128 v[188:191], v156 offset:4096
	ds_read_b128 v[192:195], v156 offset:5120
	ds_read_b128 v[196:199], v156 offset:6144
	ds_read_b128 v[200:203], v156 offset:7168
	s_add_u32 s34, s34, 0x100080
	s_addc_u32 s35, s35, 0
	s_add_i32 m0, s0, 0xc000
	s_nop 0
	global_load_lds_dwordx4 v152, s[34:35]
	s_nop 0
	s_add_i32 m0, s0, 0xe000
	s_nop 0
	global_load_lds_dwordx4 v153, s[34:35]
	s_waitcnt vmcnt(8)
	s_waitcnt lgkmcnt(0)
	s_barrier
	s_setprio 1
	v_mfma_f32_16x16x32_bf16 v[132:135], v[120:123], v[172:175], v[132:135]
	v_mfma_f32_16x16x32_bf16 v[128:131], v[136:139], v[172:175], v[128:131]
	v_mfma_f32_16x16x32_bf16 v[116:119], v[120:123], v[180:183], v[116:119]
	v_mfma_f32_16x16x32_bf16 v[112:115], v[136:139], v[180:183], v[112:115]
	v_mfma_f32_16x16x32_bf16 v[92:95], v[120:123], v[188:191], v[92:95]
	v_mfma_f32_16x16x32_bf16 v[88:91], v[136:139], v[188:191], v[88:91]
	v_mfma_f32_16x16x32_bf16 v[76:79], v[120:123], v[196:199], v[76:79]
	v_mfma_f32_16x16x32_bf16 v[72:75], v[136:139], v[196:199], v[72:75]
	v_mfma_f32_16x16x32_bf16 v[132:135], v[124:127], v[176:179], v[132:135]
	v_mfma_f32_16x16x32_bf16 v[128:131], v[140:143], v[176:179], v[128:131]
	v_mfma_f32_16x16x32_bf16 v[116:119], v[124:127], v[184:187], v[116:119]
	v_mfma_f32_16x16x32_bf16 v[112:115], v[140:143], v[184:187], v[112:115]
	v_mfma_f32_16x16x32_bf16 v[92:95], v[124:127], v[192:195], v[92:95]
	v_mfma_f32_16x16x32_bf16 v[88:91], v[140:143], v[192:195], v[88:91]
	v_mfma_f32_16x16x32_bf16 v[76:79], v[124:127], v[200:203], v[76:79]
	v_mfma_f32_16x16x32_bf16 v[72:75], v[140:143], v[200:203], v[72:75]
	v_mfma_f32_16x16x32_bf16 v[108:111], v[148:151], v[172:175], v[108:111]
	v_mfma_f32_16x16x32_bf16 v[104:107], v[164:167], v[172:175], v[104:107]
	v_mfma_f32_16x16x32_bf16 v[100:103], v[148:151], v[180:183], v[100:103]
	v_mfma_f32_16x16x32_bf16 v[96:99], v[164:167], v[180:183], v[96:99]
	v_mfma_f32_16x16x32_bf16 v[84:87], v[148:151], v[188:191], v[84:87]
	v_mfma_f32_16x16x32_bf16 v[80:83], v[164:167], v[188:191], v[80:83]
	v_mfma_f32_16x16x32_bf16 v[68:71], v[148:151], v[196:199], v[68:71]
	v_mfma_f32_16x16x32_bf16 v[64:67], v[164:167], v[196:199], v[64:67]
	v_mfma_f32_16x16x32_bf16 v[108:111], v[160:163], v[176:179], v[108:111]
	v_mfma_f32_16x16x32_bf16 v[104:107], v[168:171], v[176:179], v[104:107]
	v_mfma_f32_16x16x32_bf16 v[100:103], v[160:163], v[184:187], v[100:103]
	v_mfma_f32_16x16x32_bf16 v[96:99], v[168:171], v[184:187], v[96:99]
	v_mfma_f32_16x16x32_bf16 v[84:87], v[160:163], v[192:195], v[84:87]
	v_mfma_f32_16x16x32_bf16 v[80:83], v[168:171], v[192:195], v[80:83]
	v_mfma_f32_16x16x32_bf16 v[68:71], v[160:163], v[200:203], v[68:71]
	v_mfma_f32_16x16x32_bf16 v[64:67], v[168:171], v[200:203], v[64:67]
	s_setprio 0
	s_barrier
	ds_read_b128 v[172:175], v156 offset:16384
	ds_read_b128 v[176:179], v156 offset:17408
	ds_read_b128 v[180:183], v156 offset:18432
	ds_read_b128 v[184:187], v156 offset:19456
	ds_read_b128 v[188:191], v156 offset:20480
	ds_read_b128 v[192:195], v156 offset:21504
	ds_read_b128 v[196:199], v156 offset:22528
	ds_read_b128 v[200:203], v156 offset:23552
	s_add_i32 m0, s0, 0x10000
	s_nop 0
	global_load_lds_dwordx4 v152, s[40:41]
	s_nop 0
	s_add_i32 m0, s0, 0x12000
	s_nop 0
	global_load_lds_dwordx4 v153, s[40:41]
	s_add_u32 s34, s40, 0x100000
	s_addc_u32 s35, s41, 0
	s_add_i32 m0, s0, 0x14000
	s_nop 0
	global_load_lds_dwordx4 v152, s[34:35]
	s_nop 0
	s_add_i32 m0, s0, 0x16000
	s_nop 0
	global_load_lds_dwordx4 v153, s[34:35]
	s_nop 0
	s_add_i32 m0, s0, 0
	s_nop 0
	global_load_lds_dwordx4 v152, s[42:43]
	s_nop 0
	s_add_i32 m0, s0, 0x2000
	s_nop 0
	global_load_lds_dwordx4 v153, s[42:43]
	s_waitcnt vmcnt(8)
	s_waitcnt lgkmcnt(0)
	s_barrier
	s_setprio 1
	v_mfma_f32_16x16x32_bf16 v[60:63], v[120:123], v[172:175], v[60:63]
	v_mfma_f32_16x16x32_bf16 v[56:59], v[136:139], v[172:175], v[56:59]
	v_mfma_f32_16x16x32_bf16 v[52:55], v[120:123], v[180:183], v[52:55]
	v_mfma_f32_16x16x32_bf16 v[44:47], v[136:139], v[180:183], v[44:47]
	v_mfma_f32_16x16x32_bf16 v[36:39], v[120:123], v[188:191], v[36:39]
	v_mfma_f32_16x16x32_bf16 v[28:31], v[136:139], v[188:191], v[28:31]
	v_mfma_f32_16x16x32_bf16 v[16:19], v[120:123], v[196:199], v[16:19]
	v_mfma_f32_16x16x32_bf16 v[8:11], v[136:139], v[196:199], v[8:11]
	v_mfma_f32_16x16x32_bf16 v[60:63], v[124:127], v[176:179], v[60:63]
	v_mfma_f32_16x16x32_bf16 v[56:59], v[140:143], v[176:179], v[56:59]
	v_mfma_f32_16x16x32_bf16 v[52:55], v[124:127], v[184:187], v[52:55]
	v_mfma_f32_16x16x32_bf16 v[44:47], v[140:143], v[184:187], v[44:47]
	v_mfma_f32_16x16x32_bf16 v[36:39], v[124:127], v[192:195], v[36:39]
	v_mfma_f32_16x16x32_bf16 v[28:31], v[140:143], v[192:195], v[28:31]
	v_mfma_f32_16x16x32_bf16 v[16:19], v[124:127], v[200:203], v[16:19]
	v_mfma_f32_16x16x32_bf16 v[8:11], v[140:143], v[200:203], v[8:11]
	v_mfma_f32_16x16x32_bf16 v[48:51], v[148:151], v[172:175], v[48:51]
	v_mfma_f32_16x16x32_bf16 v[40:43], v[164:167], v[172:175], v[40:43]
	v_mfma_f32_16x16x32_bf16 v[32:35], v[148:151], v[180:183], v[32:35]
	v_mfma_f32_16x16x32_bf16 v[24:27], v[164:167], v[180:183], v[24:27]
	v_mfma_f32_16x16x32_bf16 v[20:23], v[148:151], v[188:191], v[20:23]
	v_mfma_f32_16x16x32_bf16 v[12:15], v[164:167], v[188:191], v[12:15]
	v_mfma_f32_16x16x32_bf16 v[4:7], v[148:151], v[196:199], v[4:7]
	v_mfma_f32_16x16x32_bf16 v[0:3], v[164:167], v[196:199], v[0:3]
	v_mfma_f32_16x16x32_bf16 v[48:51], v[160:163], v[176:179], v[48:51]
	v_mfma_f32_16x16x32_bf16 v[40:43], v[168:171], v[176:179], v[40:43]
	v_mfma_f32_16x16x32_bf16 v[32:35], v[160:163], v[184:187], v[32:35]
	v_mfma_f32_16x16x32_bf16 v[24:27], v[168:171], v[184:187], v[24:27]
	v_mfma_f32_16x16x32_bf16 v[20:23], v[160:163], v[192:195], v[20:23]
	v_mfma_f32_16x16x32_bf16 v[12:15], v[168:171], v[192:195], v[12:15]
	v_mfma_f32_16x16x32_bf16 v[4:7], v[160:163], v[200:203], v[4:7]
	v_mfma_f32_16x16x32_bf16 v[0:3], v[168:171], v[200:203], v[0:3]
	s_setprio 0
	s_barrier
	ds_read_b128 v[120:123], v157
	ds_read_b128 v[124:127], v157 offset:1024
	ds_read_b128 v[136:139], v157 offset:2048
	ds_read_b128 v[140:143], v157 offset:3072
	ds_read_b128 v[148:151], v158
	ds_read_b128 v[160:163], v158 offset:1024
	ds_read_b128 v[164:167], v158 offset:2048
	ds_read_b128 v[168:171], v158 offset:3072
	ds_read_b128 v[172:175], v156 offset:32768
	ds_read_b128 v[176:179], v156 offset:33792
	ds_read_b128 v[180:183], v156 offset:34816
	ds_read_b128 v[184:187], v156 offset:35840
	ds_read_b128 v[188:191], v156 offset:36864
	ds_read_b128 v[192:195], v156 offset:37888
	ds_read_b128 v[196:199], v156 offset:38912
	ds_read_b128 v[200:203], v156 offset:39936
	s_add_u32 s34, s42, 0x100000
	s_addc_u32 s35, s43, 0
	s_add_i32 m0, s0, 0x4000
	s_nop 0
	global_load_lds_dwordx4 v152, s[34:35]
	s_nop 0
	s_add_i32 m0, s0, 0x6000
	s_nop 0
	global_load_lds_dwordx4 v153, s[34:35]
	s_waitcnt vmcnt(8)
	s_waitcnt lgkmcnt(0)
	s_barrier
	s_setprio 1
	v_mfma_f32_16x16x32_bf16 v[132:135], v[120:123], v[172:175], v[132:135]
	v_mfma_f32_16x16x32_bf16 v[128:131], v[136:139], v[172:175], v[128:131]
	v_mfma_f32_16x16x32_bf16 v[116:119], v[120:123], v[180:183], v[116:119]
	v_mfma_f32_16x16x32_bf16 v[112:115], v[136:139], v[180:183], v[112:115]
	v_mfma_f32_16x16x32_bf16 v[92:95], v[120:123], v[188:191], v[92:95]
	v_mfma_f32_16x16x32_bf16 v[88:91], v[136:139], v[188:191], v[88:91]
	v_mfma_f32_16x16x32_bf16 v[76:79], v[120:123], v[196:199], v[76:79]
	v_mfma_f32_16x16x32_bf16 v[72:75], v[136:139], v[196:199], v[72:75]
	v_mfma_f32_16x16x32_bf16 v[132:135], v[124:127], v[176:179], v[132:135]
	v_mfma_f32_16x16x32_bf16 v[128:131], v[140:143], v[176:179], v[128:131]
	v_mfma_f32_16x16x32_bf16 v[116:119], v[124:127], v[184:187], v[116:119]
	v_mfma_f32_16x16x32_bf16 v[112:115], v[140:143], v[184:187], v[112:115]
	v_mfma_f32_16x16x32_bf16 v[92:95], v[124:127], v[192:195], v[92:95]
	v_mfma_f32_16x16x32_bf16 v[88:91], v[140:143], v[192:195], v[88:91]
	v_mfma_f32_16x16x32_bf16 v[76:79], v[124:127], v[200:203], v[76:79]
	v_mfma_f32_16x16x32_bf16 v[72:75], v[140:143], v[200:203], v[72:75]
	v_mfma_f32_16x16x32_bf16 v[108:111], v[148:151], v[172:175], v[108:111]
	v_mfma_f32_16x16x32_bf16 v[104:107], v[164:167], v[172:175], v[104:107]
	v_mfma_f32_16x16x32_bf16 v[100:103], v[148:151], v[180:183], v[100:103]
	v_mfma_f32_16x16x32_bf16 v[96:99], v[164:167], v[180:183], v[96:99]
	v_mfma_f32_16x16x32_bf16 v[84:87], v[148:151], v[188:191], v[84:87]
	v_mfma_f32_16x16x32_bf16 v[80:83], v[164:167], v[188:191], v[80:83]
	v_mfma_f32_16x16x32_bf16 v[68:71], v[148:151], v[196:199], v[68:71]
	v_mfma_f32_16x16x32_bf16 v[64:67], v[164:167], v[196:199], v[64:67]
	v_mfma_f32_16x16x32_bf16 v[108:111], v[160:163], v[176:179], v[108:111]
	v_mfma_f32_16x16x32_bf16 v[104:107], v[168:171], v[176:179], v[104:107]
	v_mfma_f32_16x16x32_bf16 v[100:103], v[160:163], v[184:187], v[100:103]
	v_mfma_f32_16x16x32_bf16 v[96:99], v[168:171], v[184:187], v[96:99]
	v_mfma_f32_16x16x32_bf16 v[84:87], v[160:163], v[192:195], v[84:87]
	v_mfma_f32_16x16x32_bf16 v[80:83], v[168:171], v[192:195], v[80:83]
	v_mfma_f32_16x16x32_bf16 v[68:71], v[160:163], v[200:203], v[68:71]
	v_mfma_f32_16x16x32_bf16 v[64:67], v[168:171], v[200:203], v[64:67]
	s_setprio 0
	s_barrier
	s_add_u32 s34, s40, 0x80
	ds_read_b128 v[172:175], v156 offset:49152
	ds_read_b128 v[176:179], v156 offset:50176
	ds_read_b128 v[180:183], v156 offset:51200
	ds_read_b128 v[184:187], v156 offset:52224
	ds_read_b128 v[188:191], v156 offset:53248
	ds_read_b128 v[192:195], v156 offset:54272
	ds_read_b128 v[196:199], v156 offset:55296
	ds_read_b128 v[200:203], v156 offset:56320
	s_addc_u32 s35, s41, 0
	s_add_i32 m0, s0, 0x18000
	s_nop 0
	global_load_lds_dwordx4 v152, s[34:35]
	s_nop 0
	s_add_i32 m0, s0, 0x1a000
	s_nop 0
	global_load_lds_dwordx4 v153, s[34:35]
	s_add_u32 s34, s40, 0x100080
	s_addc_u32 s35, s41, 0
	s_add_i32 m0, s0, 0x1c000
	s_nop 0
	global_load_lds_dwordx4 v152, s[34:35]
	s_nop 0
	s_add_i32 m0, s0, 0x1e000
	s_nop 0
	global_load_lds_dwordx4 v153, s[34:35]
	s_nop 0
	s_add_i32 m0, s0, 0x8000
	s_nop 0
	global_load_lds_dwordx4 v152, s[38:39]
	s_nop 0
	s_add_i32 m0, s0, 0xa000
	s_nop 0
	global_load_lds_dwordx4 v153, s[38:39]
	s_waitcnt vmcnt(8)
	s_waitcnt lgkmcnt(0)
	s_barrier
	s_setprio 1
	v_mfma_f32_16x16x32_bf16 v[60:63], v[120:123], v[172:175], v[60:63]
	v_mfma_f32_16x16x32_bf16 v[56:59], v[136:139], v[172:175], v[56:59]
	v_mfma_f32_16x16x32_bf16 v[52:55], v[120:123], v[180:183], v[52:55]
	v_mfma_f32_16x16x32_bf16 v[44:47], v[136:139], v[180:183], v[44:47]
	v_mfma_f32_16x16x32_bf16 v[36:39], v[120:123], v[188:191], v[36:39]
	v_mfma_f32_16x16x32_bf16 v[28:31], v[136:139], v[188:191], v[28:31]
	v_mfma_f32_16x16x32_bf16 v[16:19], v[120:123], v[196:199], v[16:19]
	v_mfma_f32_16x16x32_bf16 v[8:11], v[136:139], v[196:199], v[8:11]
	v_mfma_f32_16x16x32_bf16 v[60:63], v[124:127], v[176:179], v[60:63]
	v_mfma_f32_16x16x32_bf16 v[56:59], v[140:143], v[176:179], v[56:59]
	v_mfma_f32_16x16x32_bf16 v[52:55], v[124:127], v[184:187], v[52:55]
	v_mfma_f32_16x16x32_bf16 v[44:47], v[140:143], v[184:187], v[44:47]
	v_mfma_f32_16x16x32_bf16 v[36:39], v[124:127], v[192:195], v[36:39]
	v_mfma_f32_16x16x32_bf16 v[28:31], v[140:143], v[192:195], v[28:31]
	v_mfma_f32_16x16x32_bf16 v[16:19], v[124:127], v[200:203], v[16:19]
	v_mfma_f32_16x16x32_bf16 v[8:11], v[140:143], v[200:203], v[8:11]
	v_mfma_f32_16x16x32_bf16 v[48:51], v[148:151], v[172:175], v[48:51]
	v_mfma_f32_16x16x32_bf16 v[40:43], v[164:167], v[172:175], v[40:43]
	v_mfma_f32_16x16x32_bf16 v[32:35], v[148:151], v[180:183], v[32:35]
	v_mfma_f32_16x16x32_bf16 v[24:27], v[164:167], v[180:183], v[24:27]
	v_mfma_f32_16x16x32_bf16 v[20:23], v[148:151], v[188:191], v[20:23]
	v_mfma_f32_16x16x32_bf16 v[12:15], v[164:167], v[188:191], v[12:15]
	v_mfma_f32_16x16x32_bf16 v[4:7], v[148:151], v[196:199], v[4:7]
	v_mfma_f32_16x16x32_bf16 v[0:3], v[164:167], v[196:199], v[0:3]
	v_mfma_f32_16x16x32_bf16 v[48:51], v[160:163], v[176:179], v[48:51]
	v_mfma_f32_16x16x32_bf16 v[40:43], v[168:171], v[176:179], v[40:43]
	v_mfma_f32_16x16x32_bf16 v[32:35], v[160:163], v[184:187], v[32:35]
	v_mfma_f32_16x16x32_bf16 v[24:27], v[168:171], v[184:187], v[24:27]
	v_mfma_f32_16x16x32_bf16 v[20:23], v[160:163], v[192:195], v[20:23]
	v_mfma_f32_16x16x32_bf16 v[12:15], v[168:171], v[192:195], v[12:15]
	v_mfma_f32_16x16x32_bf16 v[4:7], v[160:163], v[200:203], v[4:7]
	v_mfma_f32_16x16x32_bf16 v[0:3], v[168:171], v[200:203], v[0:3]
	s_setprio 0
	s_barrier
	s_add_i32 s62, s62, 2
	s_add_u32 s60, s60, 0x100
	s_addc_u32 s61, s61, 0
	s_cmp_gt_u32 s62, 61
	s_mov_b64 s[34:35], s[36:37]
	s_cbranch_scc0 .LBB0_1605
	s_and_b64 vcc, exec, s[12:13]
	s_cbranch_vccz .LBB0_1608
	s_barrier

.LBB0_1681:
	ds_read_b128 v[128:131], v158
	ds_read_b128 v[132:135], v158 offset:1024
	ds_read_b128 v[136:139], v158 offset:2048
	ds_read_b128 v[140:143], v158 offset:3072
	ds_read_b128 v[148:151], v159
	ds_read_b128 v[152:155], v159 offset:1024
	ds_read_b128 v[164:167], v159 offset:2048
	ds_read_b128 v[168:171], v159 offset:3072
	s_add_u32 s24, s22, 0x100
	s_addc_u32 s25, s23, 0
	s_cmpk_eq_i32 s45, 0xfc
	s_cselect_b32 s30, s41, s24
	s_cselect_b32 s31, s15, s25
	s_cselect_b32 s28, s42, s43
	s_cselect_b32 s29, s13, s44
	s_add_u32 s26, s30, 0x80
	s_addc_u32 s27, s31, 0
	ds_read_b128 v[172:175], v160
	ds_read_b128 v[176:179], v160 offset:1024
	ds_read_b128 v[180:183], v160 offset:2048
	ds_read_b128 v[184:187], v160 offset:3072
	ds_read_b128 v[188:191], v160 offset:4096
	ds_read_b128 v[192:195], v160 offset:5120
	ds_read_b128 v[196:199], v160 offset:6144
	ds_read_b128 v[200:203], v160 offset:7168
	s_add_u32 s22, s22, 0x400080
	s_addc_u32 s23, s23, 0
	s_add_i32 m0, s33, 0xc000
	s_nop 0
	global_load_lds_dwordx4 v156, s[22:23]
	s_nop 0
	s_add_i32 m0, s33, 0xe000
	s_nop 0
	global_load_lds_dwordx4 v157, s[22:23]
	s_waitcnt vmcnt(8)
	s_waitcnt lgkmcnt(0)
	s_barrier
	s_setprio 1
	v_mfma_f32_16x16x32_bf16 v[124:127], v[128:131], v[172:175], v[124:127]
	v_mfma_f32_16x16x32_bf16 v[120:123], v[136:139], v[172:175], v[120:123]
	v_mfma_f32_16x16x32_bf16 v[116:119], v[128:131], v[180:183], v[116:119]
	v_mfma_f32_16x16x32_bf16 v[112:115], v[136:139], v[180:183], v[112:115]
	v_mfma_f32_16x16x32_bf16 v[96:99], v[128:131], v[188:191], v[96:99]
	v_mfma_f32_16x16x32_bf16 v[88:91], v[136:139], v[188:191], v[88:91]
	v_mfma_f32_16x16x32_bf16 v[80:83], v[128:131], v[196:199], v[80:83]
	v_mfma_f32_16x16x32_bf16 v[72:75], v[136:139], v[196:199], v[72:75]
	v_mfma_f32_16x16x32_bf16 v[124:127], v[132:135], v[176:179], v[124:127]
	v_mfma_f32_16x16x32_bf16 v[120:123], v[140:143], v[176:179], v[120:123]
	v_mfma_f32_16x16x32_bf16 v[116:119], v[132:135], v[184:187], v[116:119]
	v_mfma_f32_16x16x32_bf16 v[112:115], v[140:143], v[184:187], v[112:115]
	v_mfma_f32_16x16x32_bf16 v[96:99], v[132:135], v[192:195], v[96:99]
	v_mfma_f32_16x16x32_bf16 v[88:91], v[140:143], v[192:195], v[88:91]
	v_mfma_f32_16x16x32_bf16 v[80:83], v[132:135], v[200:203], v[80:83]
	v_mfma_f32_16x16x32_bf16 v[72:75], v[140:143], v[200:203], v[72:75]
	v_mfma_f32_16x16x32_bf16 v[108:111], v[148:151], v[172:175], v[108:111]
	v_mfma_f32_16x16x32_bf16 v[104:107], v[164:167], v[172:175], v[104:107]
	v_mfma_f32_16x16x32_bf16 v[100:103], v[148:151], v[180:183], v[100:103]
	v_mfma_f32_16x16x32_bf16 v[92:95], v[164:167], v[180:183], v[92:95]
	v_mfma_f32_16x16x32_bf16 v[84:87], v[148:151], v[188:191], v[84:87]
	v_mfma_f32_16x16x32_bf16 v[76:79], v[164:167], v[188:191], v[76:79]
	v_mfma_f32_16x16x32_bf16 v[68:71], v[148:151], v[196:199], v[68:71]
	v_mfma_f32_16x16x32_bf16 v[64:67], v[164:167], v[196:199], v[64:67]
	v_mfma_f32_16x16x32_bf16 v[108:111], v[152:155], v[176:179], v[108:111]
	v_mfma_f32_16x16x32_bf16 v[104:107], v[168:171], v[176:179], v[104:107]
	v_mfma_f32_16x16x32_bf16 v[100:103], v[152:155], v[184:187], v[100:103]
	v_mfma_f32_16x16x32_bf16 v[92:95], v[168:171], v[184:187], v[92:95]
	v_mfma_f32_16x16x32_bf16 v[84:87], v[152:155], v[192:195], v[84:87]
	v_mfma_f32_16x16x32_bf16 v[76:79], v[168:171], v[192:195], v[76:79]
	v_mfma_f32_16x16x32_bf16 v[68:71], v[152:155], v[200:203], v[68:71]
	v_mfma_f32_16x16x32_bf16 v[64:67], v[168:171], v[200:203], v[64:67]
	s_setprio 0
	s_barrier
	ds_read_b128 v[172:175], v160 offset:16384
	ds_read_b128 v[176:179], v160 offset:17408
	ds_read_b128 v[180:183], v160 offset:18432
	ds_read_b128 v[184:187], v160 offset:19456
	ds_read_b128 v[188:191], v160 offset:20480
	ds_read_b128 v[192:195], v160 offset:21504
	ds_read_b128 v[196:199], v160 offset:22528
	ds_read_b128 v[200:203], v160 offset:23552
	s_add_i32 m0, s33, 0x10000
	s_nop 0
	global_load_lds_dwordx4 v156, s[28:29]
	s_nop 0
	s_add_i32 m0, s33, 0x12000
	s_nop 0
	global_load_lds_dwordx4 v157, s[28:29]
	s_add_u32 s22, s28, 0x400000
	s_addc_u32 s23, s29, 0
	s_add_i32 m0, s33, 0x14000
	s_nop 0
	global_load_lds_dwordx4 v156, s[22:23]
	s_nop 0
	s_add_i32 m0, s33, 0x16000
	s_nop 0
	global_load_lds_dwordx4 v157, s[22:23]
	s_nop 0
	s_add_i32 m0, s33, 0
	s_nop 0
	global_load_lds_dwordx4 v156, s[30:31]
	s_nop 0
	s_add_i32 m0, s33, 0x2000
	s_nop 0
	global_load_lds_dwordx4 v157, s[30:31]
	s_waitcnt vmcnt(8)
	s_waitcnt lgkmcnt(0)
	s_barrier
	s_setprio 1
	v_mfma_f32_16x16x32_bf16 v[60:63], v[128:131], v[172:175], v[60:63]
	v_mfma_f32_16x16x32_bf16 v[56:59], v[136:139], v[172:175], v[56:59]
	v_mfma_f32_16x16x32_bf16 v[48:51], v[128:131], v[180:183], v[48:51]
	v_mfma_f32_16x16x32_bf16 v[40:43], v[136:139], v[180:183], v[40:43]
	v_mfma_f32_16x16x32_bf16 v[32:35], v[128:131], v[188:191], v[32:35]
	v_mfma_f32_16x16x32_bf16 v[24:27], v[136:139], v[188:191], v[24:27]
	v_mfma_f32_16x16x32_bf16 v[16:19], v[128:131], v[196:199], v[16:19]
	v_mfma_f32_16x16x32_bf16 v[8:11], v[136:139], v[196:199], v[8:11]
	v_mfma_f32_16x16x32_bf16 v[60:63], v[132:135], v[176:179], v[60:63]
	v_mfma_f32_16x16x32_bf16 v[56:59], v[140:143], v[176:179], v[56:59]
	v_mfma_f32_16x16x32_bf16 v[48:51], v[132:135], v[184:187], v[48:51]
	v_mfma_f32_16x16x32_bf16 v[40:43], v[140:143], v[184:187], v[40:43]
	v_mfma_f32_16x16x32_bf16 v[32:35], v[132:135], v[192:195], v[32:35]
	v_mfma_f32_16x16x32_bf16 v[24:27], v[140:143], v[192:195], v[24:27]
	v_mfma_f32_16x16x32_bf16 v[16:19], v[132:135], v[200:203], v[16:19]
	v_mfma_f32_16x16x32_bf16 v[8:11], v[140:143], v[200:203], v[8:11]
	v_mfma_f32_16x16x32_bf16 v[52:55], v[148:151], v[172:175], v[52:55]
	v_mfma_f32_16x16x32_bf16 v[44:47], v[164:167], v[172:175], v[44:47]
	v_mfma_f32_16x16x32_bf16 v[36:39], v[148:151], v[180:183], v[36:39]
	v_mfma_f32_16x16x32_bf16 v[28:31], v[164:167], v[180:183], v[28:31]
	v_mfma_f32_16x16x32_bf16 v[20:23], v[148:151], v[188:191], v[20:23]
	v_mfma_f32_16x16x32_bf16 v[12:15], v[164:167], v[188:191], v[12:15]
	v_mfma_f32_16x16x32_bf16 v[4:7], v[148:151], v[196:199], v[4:7]
	v_mfma_f32_16x16x32_bf16 v[0:3], v[164:167], v[196:199], v[0:3]
	v_mfma_f32_16x16x32_bf16 v[52:55], v[152:155], v[176:179], v[52:55]
	v_mfma_f32_16x16x32_bf16 v[44:47], v[168:171], v[176:179], v[44:47]
	v_mfma_f32_16x16x32_bf16 v[36:39], v[152:155], v[184:187], v[36:39]
	v_mfma_f32_16x16x32_bf16 v[28:31], v[168:171], v[184:187], v[28:31]
	v_mfma_f32_16x16x32_bf16 v[20:23], v[152:155], v[192:195], v[20:23]
	v_mfma_f32_16x16x32_bf16 v[12:15], v[168:171], v[192:195], v[12:15]
	v_mfma_f32_16x16x32_bf16 v[4:7], v[152:155], v[200:203], v[4:7]
	v_mfma_f32_16x16x32_bf16 v[0:3], v[168:171], v[200:203], v[0:3]
	s_setprio 0
	s_barrier
	ds_read_b128 v[128:131], v161
	ds_read_b128 v[132:135], v161 offset:1024
	ds_read_b128 v[136:139], v161 offset:2048
	ds_read_b128 v[140:143], v161 offset:3072
	ds_read_b128 v[148:151], v162
	ds_read_b128 v[152:155], v162 offset:1024
	ds_read_b128 v[164:167], v162 offset:2048
	ds_read_b128 v[168:171], v162 offset:3072
	ds_read_b128 v[172:175], v160 offset:32768
	ds_read_b128 v[176:179], v160 offset:33792
	ds_read_b128 v[180:183], v160 offset:34816
	ds_read_b128 v[184:187], v160 offset:35840
	ds_read_b128 v[188:191], v160 offset:36864
	ds_read_b128 v[192:195], v160 offset:37888
	ds_read_b128 v[196:199], v160 offset:38912
	ds_read_b128 v[200:203], v160 offset:39936
	s_add_u32 s22, s30, 0x400000
	s_addc_u32 s23, s31, 0
	s_add_i32 m0, s33, 0x4000
	s_nop 0
	global_load_lds_dwordx4 v156, s[22:23]
	s_nop 0
	s_add_i32 m0, s33, 0x6000
	s_nop 0
	global_load_lds_dwordx4 v157, s[22:23]
	s_waitcnt vmcnt(8)
	s_waitcnt lgkmcnt(0)
	s_barrier
	s_setprio 1
	v_mfma_f32_16x16x32_bf16 v[124:127], v[128:131], v[172:175], v[124:127]
	v_mfma_f32_16x16x32_bf16 v[120:123], v[136:139], v[172:175], v[120:123]
	v_mfma_f32_16x16x32_bf16 v[116:119], v[128:131], v[180:183], v[116:119]
	v_mfma_f32_16x16x32_bf16 v[112:115], v[136:139], v[180:183], v[112:115]
	v_mfma_f32_16x16x32_bf16 v[96:99], v[128:131], v[188:191], v[96:99]
	v_mfma_f32_16x16x32_bf16 v[88:91], v[136:139], v[188:191], v[88:91]
	v_mfma_f32_16x16x32_bf16 v[80:83], v[128:131], v[196:199], v[80:83]
	v_mfma_f32_16x16x32_bf16 v[72:75], v[136:139], v[196:199], v[72:75]
	v_mfma_f32_16x16x32_bf16 v[124:127], v[132:135], v[176:179], v[124:127]
	v_mfma_f32_16x16x32_bf16 v[120:123], v[140:143], v[176:179], v[120:123]
	v_mfma_f32_16x16x32_bf16 v[116:119], v[132:135], v[184:187], v[116:119]
	v_mfma_f32_16x16x32_bf16 v[112:115], v[140:143], v[184:187], v[112:115]
	v_mfma_f32_16x16x32_bf16 v[96:99], v[132:135], v[192:195], v[96:99]
	v_mfma_f32_16x16x32_bf16 v[88:91], v[140:143], v[192:195], v[88:91]
	v_mfma_f32_16x16x32_bf16 v[80:83], v[132:135], v[200:203], v[80:83]
	v_mfma_f32_16x16x32_bf16 v[72:75], v[140:143], v[200:203], v[72:75]
	v_mfma_f32_16x16x32_bf16 v[108:111], v[148:151], v[172:175], v[108:111]
	v_mfma_f32_16x16x32_bf16 v[104:107], v[164:167], v[172:175], v[104:107]
	v_mfma_f32_16x16x32_bf16 v[100:103], v[148:151], v[180:183], v[100:103]
	v_mfma_f32_16x16x32_bf16 v[92:95], v[164:167], v[180:183], v[92:95]
	v_mfma_f32_16x16x32_bf16 v[84:87], v[148:151], v[188:191], v[84:87]
	v_mfma_f32_16x16x32_bf16 v[76:79], v[164:167], v[188:191], v[76:79]
	v_mfma_f32_16x16x32_bf16 v[68:71], v[148:151], v[196:199], v[68:71]
	v_mfma_f32_16x16x32_bf16 v[64:67], v[164:167], v[196:199], v[64:67]
	v_mfma_f32_16x16x32_bf16 v[108:111], v[152:155], v[176:179], v[108:111]
	v_mfma_f32_16x16x32_bf16 v[104:107], v[168:171], v[176:179], v[104:107]
	v_mfma_f32_16x16x32_bf16 v[100:103], v[152:155], v[184:187], v[100:103]
	v_mfma_f32_16x16x32_bf16 v[92:95], v[168:171], v[184:187], v[92:95]
	v_mfma_f32_16x16x32_bf16 v[84:87], v[152:155], v[192:195], v[84:87]
	v_mfma_f32_16x16x32_bf16 v[76:79], v[168:171], v[192:195], v[76:79]
	v_mfma_f32_16x16x32_bf16 v[68:71], v[152:155], v[200:203], v[68:71]
	v_mfma_f32_16x16x32_bf16 v[64:67], v[168:171], v[200:203], v[64:67]
	s_setprio 0
	s_barrier
	s_add_u32 s22, s28, 0x80
	ds_read_b128 v[172:175], v160 offset:49152
	ds_read_b128 v[176:179], v160 offset:50176
	ds_read_b128 v[180:183], v160 offset:51200
	ds_read_b128 v[184:187], v160 offset:52224
	ds_read_b128 v[188:191], v160 offset:53248
	ds_read_b128 v[192:195], v160 offset:54272
	ds_read_b128 v[196:199], v160 offset:55296
	ds_read_b128 v[200:203], v160 offset:56320
	s_addc_u32 s23, s29, 0
	s_add_i32 m0, s33, 0x18000
	s_nop 0
	global_load_lds_dwordx4 v156, s[22:23]
	s_nop 0
	s_add_i32 m0, s33, 0x1a000
	s_nop 0
	global_load_lds_dwordx4 v157, s[22:23]
	s_add_u32 s22, s28, 0x400080
	s_addc_u32 s23, s29, 0
	s_add_i32 m0, s33, 0x1c000
	s_nop 0
	global_load_lds_dwordx4 v156, s[22:23]
	s_nop 0
	s_add_i32 m0, s33, 0x1e000
	s_nop 0
	global_load_lds_dwordx4 v157, s[22:23]
	s_nop 0
	s_add_i32 m0, s33, 0x8000
	s_nop 0
	global_load_lds_dwordx4 v156, s[26:27]
	s_nop 0
	s_add_i32 m0, s33, 0xa000
	s_nop 0
	global_load_lds_dwordx4 v157, s[26:27]
	s_waitcnt vmcnt(8)
	s_waitcnt lgkmcnt(0)
	s_barrier
	s_setprio 1
	v_mfma_f32_16x16x32_bf16 v[60:63], v[128:131], v[172:175], v[60:63]
	v_mfma_f32_16x16x32_bf16 v[56:59], v[136:139], v[172:175], v[56:59]
	v_mfma_f32_16x16x32_bf16 v[48:51], v[128:131], v[180:183], v[48:51]
	v_mfma_f32_16x16x32_bf16 v[40:43], v[136:139], v[180:183], v[40:43]
	v_mfma_f32_16x16x32_bf16 v[32:35], v[128:131], v[188:191], v[32:35]
	v_mfma_f32_16x16x32_bf16 v[24:27], v[136:139], v[188:191], v[24:27]
	v_mfma_f32_16x16x32_bf16 v[16:19], v[128:131], v[196:199], v[16:19]
	v_mfma_f32_16x16x32_bf16 v[8:11], v[136:139], v[196:199], v[8:11]
	v_mfma_f32_16x16x32_bf16 v[60:63], v[132:135], v[176:179], v[60:63]
	v_mfma_f32_16x16x32_bf16 v[56:59], v[140:143], v[176:179], v[56:59]
	v_mfma_f32_16x16x32_bf16 v[48:51], v[132:135], v[184:187], v[48:51]
	v_mfma_f32_16x16x32_bf16 v[40:43], v[140:143], v[184:187], v[40:43]
	v_mfma_f32_16x16x32_bf16 v[32:35], v[132:135], v[192:195], v[32:35]
	v_mfma_f32_16x16x32_bf16 v[24:27], v[140:143], v[192:195], v[24:27]
	v_mfma_f32_16x16x32_bf16 v[16:19], v[132:135], v[200:203], v[16:19]
	v_mfma_f32_16x16x32_bf16 v[8:11], v[140:143], v[200:203], v[8:11]
	v_mfma_f32_16x16x32_bf16 v[52:55], v[148:151], v[172:175], v[52:55]
	v_mfma_f32_16x16x32_bf16 v[44:47], v[164:167], v[172:175], v[44:47]
	v_mfma_f32_16x16x32_bf16 v[36:39], v[148:151], v[180:183], v[36:39]
	v_mfma_f32_16x16x32_bf16 v[28:31], v[164:167], v[180:183], v[28:31]
	v_mfma_f32_16x16x32_bf16 v[20:23], v[148:151], v[188:191], v[20:23]
	v_mfma_f32_16x16x32_bf16 v[12:15], v[164:167], v[188:191], v[12:15]
	v_mfma_f32_16x16x32_bf16 v[4:7], v[148:151], v[196:199], v[4:7]
	v_mfma_f32_16x16x32_bf16 v[0:3], v[164:167], v[196:199], v[0:3]
	v_mfma_f32_16x16x32_bf16 v[52:55], v[152:155], v[176:179], v[52:55]
	v_mfma_f32_16x16x32_bf16 v[44:47], v[168:171], v[176:179], v[44:47]
	v_mfma_f32_16x16x32_bf16 v[36:39], v[152:155], v[184:187], v[36:39]
	v_mfma_f32_16x16x32_bf16 v[28:31], v[168:171], v[184:187], v[28:31]
	v_mfma_f32_16x16x32_bf16 v[20:23], v[152:155], v[192:195], v[20:23]
	v_mfma_f32_16x16x32_bf16 v[12:15], v[168:171], v[192:195], v[12:15]
	v_mfma_f32_16x16x32_bf16 v[4:7], v[152:155], v[200:203], v[4:7]
	v_mfma_f32_16x16x32_bf16 v[0:3], v[168:171], v[200:203], v[0:3]
	s_setprio 0
	s_barrier
	s_add_i32 s45, s45, 2
	s_add_u32 s43, s43, 0x100
	s_addc_u32 s44, s44, 0
	s_cmpk_gt_u32 s45, 0xfd
	s_mov_b64 s[22:23], s[24:25]
	s_cbranch_scc0 .LBB0_1681
	s_and_b64 vcc, exec, s[10:11]
	s_cbranch_vccz .LBB0_1684
	s_barrier
